# v70 + last K-loop pad nop slot filled with a hoisted SALU op (setprio flips kept)
# speedup vs baseline: 1.0086x; 1.0086x over previous
; #define PG8_STAGE(bufoff, gbase, voff) do { _Pragma("unroll") for (int _i = 0; _i < 2; ++_i) \
;         __builtin_amdgcn_global_load_lds((const unsigned*)((const char*)(gbase) + (voff)[_i]), (PG8_LAS unsigned*)(lds + (bufoff) + ldsw + _i * 8192), 16, 0, 0); } while (0)
; #define PG8_LDA(dst, b, h) do { _Pragma("unroll") for (int m = 0; m < 4; ++m) _Pragma("unroll") for (int k = 0; k < 2; ++k) dst[m][k] = *(const PG8_LAS bf16x8*)(lds + PG8_SA(b, h) + aoff + m * 2048 + k * 1024); } while (0)
; #define PG8_LDB(dst, b, h) do { _Pragma("unroll") for (int n = 0; n < 2; ++n) _Pragma("unroll") for (int k = 0; k < 2; ++k) dst[n][k] = *(const PG8_LAS bf16x8*)(lds + PG8_SB(b, h) + boff + n * 2048 + k * 1024); } while (0)
; #define PG8_MMA(ai, bj, At, Bt) do { __builtin_amdgcn_s_setprio(1); _Pragma("unroll") for (int m = 0; m < 4; ++m) _Pragma("unroll") for (int n = 0; n < 2; ++n) _Pragma("unroll") for (int k = 0; k < 2; ++k) \
;         acc[ai][bj][m][n] = __builtin_amdgcn_mfma_f32_16x16x32_bf16(Bt[n][k], At[m][k], acc[ai][bj][m][n], 0, 0, 0); __builtin_amdgcn_s_setprio(0); } while (0)
; #define PG8_WAIT_V(n) asm volatile("s_waitcnt vmcnt(" #n ")" ::: "memory")
; #define PG8_WAIT_L(n) asm volatile("s_waitcnt lgkmcnt(" #n ")" ::: "memory")
; #define PG8_BAR __builtin_amdgcn_s_barrier()
; #define PG8_SCHED __builtin_amdgcn_sched_barrier(0)
; template <class Epi, class Sched, bool ALIGN_EPI = false, bool SP2 = false>
; __device__ __forceinline__ void gemm_phase(PG8_LAS unsigned char* lds, const Gemm g, const Sched& S, const Epi& E) {
;     ...
;         for (int t = 0; t < nt; t += 2) {
;             const bool last = (t == nt - 2);
;             const char* a1 = cA + (size_t)(t + 1) * kstep;
;             const char* a2 = last ? nA : cA + (size_t)(t + 2) * kstep; const char* b2 = last ? nB : cB + (size_t)(t + 2) * kstep;
;             const char* a3 = a2 + kstep; const char* b3 = b2 + kstep;
;             if (last && has_next) S.a_ready(nxt);
;             if constexpr (SP2) {
;             PG8_LDB(B0, 0, 0); PG8_LDB(B1, 0, 1); PG8_SCHED; PG8_LDA(At, 0, 0); PG8_STAGE(PG8_SA(1, 1), a1 + hstep, voffA);
;             PG8_WAIT_V(8); PG8_WAIT_L(0); PG8_BAR; PG8_MMA(0, 0, At, B0); PG8_MMA(0, 1, At, B1); PG8_BAR; PG8_SCHED;
;             PG8_LDA(At, 0, 1); PG8_STAGE(PG8_SB(0, 0), b2, voffB); PG8_STAGE(PG8_SB(0, 1), b2 + hstep, voffB); PG8_STAGE(PG8_SA(0, 0), a2, voffA);
.LBB0_100:
	s_add_u32 s28, s8, 0xfffc0080
	s_addc_u32 s29, s9, -1
	s_add_i32 s53, 0, 0x10000
	s_cmp_eq_u32 s45, 12
	s_cselect_b32 s31, s3, s29
	s_cselect_b32 s30, s7, s28
	s_cselect_b32 s29, s11, s44
	s_cselect_b32 s28, s21, s23
	s_add_i32 s56, 0, 0x14000
	v_add_u32_e32 v144, s53, v204
	v_add_u32_e32 v160, s56, v204
	ds_read_b128 v[132:135], v144
	ds_read_b128 v[136:139], v144 offset:1024
	ds_read_b128 v[140:143], v144 offset:2048
	ds_read_b128 v[144:147], v144 offset:3072
	ds_read_b128 v[148:151], v160
	ds_read_b128 v[152:155], v160 offset:1024
	ds_read_b128 v[156:159], v160 offset:2048
	ds_read_b128 v[160:163], v160 offset:3072
	v_lshl_add_u64 v[194:195], s[8:9], 0, v[178:179]
	s_add_i32 m0, s42, 0xc000
	ds_read_b128 v[164:167], v205
	ds_read_b128 v[182:185], v205 offset:1024
	ds_read_b128 v[186:189], v205 offset:2048
	ds_read_b128 v[190:193], v205 offset:3072
	ds_read_b128 v[208:211], v205 offset:4096
	ds_read_b128 v[212:215], v205 offset:5120
	ds_read_b128 v[216:219], v205 offset:6144
	ds_read_b128 v[220:223], v205 offset:7168
	global_load_lds_dwordx4 v[194:195], off
	s_add_i32 m0, s42, 0xe000
	v_lshl_add_u64 v[194:195], s[8:9], 0, v[180:181]
	global_load_lds_dwordx4 v[194:195], off
	s_waitcnt vmcnt(8) lgkmcnt(0)
	s_barrier
	s_setprio 1
	v_mfma_f32_16x16x32_bf16 v[128:131], v[132:135], v[164:167], v[128:131]
	v_mfma_f32_16x16x32_bf16 v[124:127], v[140:143], v[164:167], v[124:127]
	v_mfma_f32_16x16x32_bf16 v[112:115], v[132:135], v[186:189], v[112:115]
	v_mfma_f32_16x16x32_bf16 v[108:111], v[140:143], v[186:189], v[108:111]
	v_mfma_f32_16x16x32_bf16 v[96:99], v[132:135], v[208:211], v[96:99]
	v_mfma_f32_16x16x32_bf16 v[92:95], v[140:143], v[208:211], v[92:95]
	v_mfma_f32_16x16x32_bf16 v[80:83], v[132:135], v[216:219], v[80:83]
	v_mfma_f32_16x16x32_bf16 v[76:79], v[140:143], v[216:219], v[76:79]
	v_mfma_f32_16x16x32_bf16 v[128:131], v[136:139], v[182:185], v[128:131]
	v_mfma_f32_16x16x32_bf16 v[124:127], v[144:147], v[182:185], v[124:127]
	v_mfma_f32_16x16x32_bf16 v[112:115], v[136:139], v[190:193], v[112:115]
	v_mfma_f32_16x16x32_bf16 v[108:111], v[144:147], v[190:193], v[108:111]
	v_mfma_f32_16x16x32_bf16 v[96:99], v[136:139], v[212:215], v[96:99]
	v_mfma_f32_16x16x32_bf16 v[92:95], v[144:147], v[212:215], v[92:95]
	v_mfma_f32_16x16x32_bf16 v[80:83], v[136:139], v[220:223], v[80:83]
	v_mfma_f32_16x16x32_bf16 v[76:79], v[144:147], v[220:223], v[76:79]
	s_setprio 0
	s_setprio 1
	v_mfma_f32_16x16x32_bf16 v[120:123], v[148:151], v[164:167], v[120:123]
	v_mfma_f32_16x16x32_bf16 v[116:119], v[156:159], v[164:167], v[116:119]
	v_mfma_f32_16x16x32_bf16 v[104:107], v[148:151], v[186:189], v[104:107]
	v_mfma_f32_16x16x32_bf16 v[100:103], v[156:159], v[186:189], v[100:103]
	v_mfma_f32_16x16x32_bf16 v[88:91], v[148:151], v[208:211], v[88:91]
	v_mfma_f32_16x16x32_bf16 v[84:87], v[156:159], v[208:211], v[84:87]
	v_mfma_f32_16x16x32_bf16 v[72:75], v[148:151], v[216:219], v[72:75]
	v_mfma_f32_16x16x32_bf16 v[68:71], v[156:159], v[216:219], v[68:71]
	v_mfma_f32_16x16x32_bf16 v[120:123], v[152:155], v[182:185], v[120:123]
	v_mfma_f32_16x16x32_bf16 v[116:119], v[160:163], v[182:185], v[116:119]
	v_mfma_f32_16x16x32_bf16 v[104:107], v[152:155], v[190:193], v[104:107]
	v_mfma_f32_16x16x32_bf16 v[100:103], v[160:163], v[190:193], v[100:103]
	v_mfma_f32_16x16x32_bf16 v[88:91], v[152:155], v[212:215], v[88:91]
	v_mfma_f32_16x16x32_bf16 v[84:87], v[160:163], v[212:215], v[84:87]
	v_mfma_f32_16x16x32_bf16 v[72:75], v[152:155], v[220:223], v[72:75]
	v_mfma_f32_16x16x32_bf16 v[68:71], v[160:163], v[220:223], v[68:71]
	s_setprio 0
	s_barrier
	s_add_i32 s53, s53, s41
	v_lshl_add_u64 v[194:195], s[28:29], 0, v[168:169]
	s_mov_b32 m0, s53
	ds_read_b128 v[164:167], v205 offset:16384
	ds_read_b128 v[182:185], v205 offset:17408
	ds_read_b128 v[186:189], v205 offset:18432
	ds_read_b128 v[190:193], v205 offset:19456
	ds_read_b128 v[208:211], v205 offset:20480
	ds_read_b128 v[212:215], v205 offset:21504
	ds_read_b128 v[216:219], v205 offset:22528
	ds_read_b128 v[220:223], v205 offset:23552
	global_load_lds_dwordx4 v[194:195], off
	s_add_i32 m0, s53, 0x2000
	s_add_u32 s54, s28, 0x40000
	v_lshl_add_u64 v[202:203], s[28:29], 0, v[172:173]
	s_addc_u32 s55, s29, 0
	s_add_i32 s53, s56, s41
	global_load_lds_dwordx4 v[202:203], off
	v_lshl_add_u64 v[224:225], s[54:55], 0, v[168:169]
	s_mov_b32 m0, s53
	v_lshl_add_u64 v[226:227], s[30:31], 0, v[170:171]
	global_load_lds_dwordx4 v[224:225], off
	s_add_i32 m0, s53, 0x2000
	v_lshl_add_u64 v[224:225], s[54:55], 0, v[172:173]
	global_load_lds_dwordx4 v[224:225], off
	s_mov_b32 m0, s42
	v_lshl_add_u64 v[224:225], s[30:31], 0, v[0:1]
	global_load_lds_dwordx4 v[224:225], off
	s_mov_b32 m0, s43
	s_add_i32 s53, 0, 0x18000
	global_load_lds_dwordx4 v[226:227], off
	s_waitcnt vmcnt(8) lgkmcnt(0)
	s_barrier
; #define PG8_STAGE(bufoff, gbase, voff) do { _Pragma("unroll") for (int _i = 0; _i < 2; ++_i) \
;         __builtin_amdgcn_global_load_lds((const unsigned*)((const char*)(gbase) + (voff)[_i]), (PG8_LAS unsigned*)(lds + (bufoff) + ldsw + _i * 8192), 16, 0, 0); } while (0)
; #define PG8_LDA(dst, b, h) do { _Pragma("unroll") for (int m = 0; m < 4; ++m) _Pragma("unroll") for (int k = 0; k < 2; ++k) dst[m][k] = *(const PG8_LAS bf16x8*)(lds + PG8_SA(b, h) + aoff + m * 2048 + k * 1024); } while (0)
; #define PG8_LDB(dst, b, h) do { _Pragma("unroll") for (int n = 0; n < 2; ++n) _Pragma("unroll") for (int k = 0; k < 2; ++k) dst[n][k] = *(const PG8_LAS bf16x8*)(lds + PG8_SB(b, h) + boff + n * 2048 + k * 1024); } while (0)
; #define PG8_MMA(ai, bj, At, Bt) do { __builtin_amdgcn_s_setprio(1); _Pragma("unroll") for (int m = 0; m < 4; ++m) _Pragma("unroll") for (int n = 0; n < 2; ++n) _Pragma("unroll") for (int k = 0; k < 2; ++k) \
;         acc[ai][bj][m][n] = __builtin_amdgcn_mfma_f32_16x16x32_bf16(Bt[n][k], At[m][k], acc[ai][bj][m][n], 0, 0, 0); __builtin_amdgcn_s_setprio(0); } while (0)
; #define PG8_WAIT_V(n) asm volatile("s_waitcnt vmcnt(" #n ")" ::: "memory")
; #define PG8_WAIT_L(n) asm volatile("s_waitcnt lgkmcnt(" #n ")" ::: "memory")
; #define PG8_BAR __builtin_amdgcn_s_barrier()
; #define PG8_SCHED __builtin_amdgcn_sched_barrier(0)
; template <class Epi, class Sched, bool ALIGN_EPI = false, bool SP2 = false>
; __device__ __forceinline__ void gemm_phase(PG8_LAS unsigned char* lds, const Gemm g, const Sched& S, const Epi& E) {
;     ...
;             PG8_WAIT_V(8); PG8_WAIT_L(0); PG8_BAR; PG8_MMA(1, 0, At, B0); PG8_MMA(1, 1, At, B1); PG8_BAR; PG8_SCHED;
;             PG8_LDB(B0, 1, 0); PG8_LDB(B1, 1, 1); PG8_SCHED; PG8_LDA(At, 1, 0); PG8_STAGE(PG8_SA(0, 1), a2 + hstep, voffA);
;             PG8_WAIT_V(8); PG8_WAIT_L(0); PG8_BAR; PG8_MMA(0, 0, At, B0); PG8_MMA(0, 1, At, B1); PG8_BAR; PG8_SCHED;
	s_setprio 1
	v_mfma_f32_16x16x32_bf16 v[64:67], v[132:135], v[164:167], v[64:67]
	v_mfma_f32_16x16x32_bf16 v[60:63], v[140:143], v[164:167], v[60:63]
	v_mfma_f32_16x16x32_bf16 v[48:51], v[132:135], v[186:189], v[48:51]
	v_mfma_f32_16x16x32_bf16 v[44:47], v[140:143], v[186:189], v[44:47]
	v_mfma_f32_16x16x32_bf16 v[32:35], v[132:135], v[208:211], v[32:35]
	v_mfma_f32_16x16x32_bf16 v[28:31], v[140:143], v[208:211], v[28:31]
	v_mfma_f32_16x16x32_bf16 v[16:19], v[132:135], v[216:219], v[16:19]
	v_mfma_f32_16x16x32_bf16 v[12:15], v[140:143], v[216:219], v[12:15]
	v_mfma_f32_16x16x32_bf16 v[64:67], v[136:139], v[182:185], v[64:67]
	v_mfma_f32_16x16x32_bf16 v[60:63], v[144:147], v[182:185], v[60:63]
	v_mfma_f32_16x16x32_bf16 v[48:51], v[136:139], v[190:193], v[48:51]
	v_mfma_f32_16x16x32_bf16 v[44:47], v[144:147], v[190:193], v[44:47]
	v_mfma_f32_16x16x32_bf16 v[32:35], v[136:139], v[212:215], v[32:35]
	v_mfma_f32_16x16x32_bf16 v[28:31], v[144:147], v[212:215], v[28:31]
	v_mfma_f32_16x16x32_bf16 v[16:19], v[136:139], v[220:223], v[16:19]
	v_mfma_f32_16x16x32_bf16 v[12:15], v[144:147], v[220:223], v[12:15]
	s_setprio 0
	s_setprio 1
	v_mfma_f32_16x16x32_bf16 v[56:59], v[148:151], v[164:167], v[56:59]
	v_mfma_f32_16x16x32_bf16 v[52:55], v[156:159], v[164:167], v[52:55]
	v_mfma_f32_16x16x32_bf16 v[40:43], v[148:151], v[186:189], v[40:43]
	v_mfma_f32_16x16x32_bf16 v[36:39], v[156:159], v[186:189], v[36:39]
	v_mfma_f32_16x16x32_bf16 v[24:27], v[148:151], v[208:211], v[24:27]
	v_mfma_f32_16x16x32_bf16 v[20:23], v[156:159], v[208:211], v[20:23]
	v_mfma_f32_16x16x32_bf16 v[8:11], v[148:151], v[216:219], v[8:11]
	v_mfma_f32_16x16x32_bf16 v[4:7], v[156:159], v[216:219], v[4:7]
	v_mfma_f32_16x16x32_bf16 v[56:59], v[152:155], v[182:185], v[56:59]
	v_mfma_f32_16x16x32_bf16 v[52:55], v[160:163], v[182:185], v[52:55]
	v_mfma_f32_16x16x32_bf16 v[40:43], v[152:155], v[190:193], v[40:43]
	v_mfma_f32_16x16x32_bf16 v[36:39], v[160:163], v[190:193], v[36:39]
	v_mfma_f32_16x16x32_bf16 v[24:27], v[152:155], v[212:215], v[24:27]
	v_mfma_f32_16x16x32_bf16 v[20:23], v[160:163], v[212:215], v[20:23]
	v_mfma_f32_16x16x32_bf16 v[8:11], v[152:155], v[220:223], v[8:11]
	v_mfma_f32_16x16x32_bf16 v[4:7], v[160:163], v[220:223], v[4:7]
	s_setprio 0
	s_barrier
	s_add_i32 s54, 0, 0x1c000
	v_add_u32_e32 v144, s53, v204
	v_add_u32_e32 v160, s54, v204
	ds_read_b128 v[132:135], v144
	ds_read_b128 v[136:139], v144 offset:1024
	ds_read_b128 v[140:143], v144 offset:2048
	ds_read_b128 v[144:147], v144 offset:3072
	ds_read_b128 v[148:151], v160
	ds_read_b128 v[152:155], v160 offset:1024
	ds_read_b128 v[156:159], v160 offset:2048
	ds_read_b128 v[160:163], v160 offset:3072
	s_add_u32 s30, s30, 0x40000
	s_addc_u32 s31, s31, 0
	s_mov_b32 m0, s46
	v_lshl_add_u64 v[228:229], s[30:31], 0, v[0:1]
	ds_read_b128 v[164:167], v205 offset:32768
	ds_read_b128 v[182:185], v205 offset:33792
	ds_read_b128 v[186:189], v205 offset:34816
	ds_read_b128 v[190:193], v205 offset:35840
	ds_read_b128 v[208:211], v205 offset:36864
	ds_read_b128 v[212:215], v205 offset:37888
	ds_read_b128 v[216:219], v205 offset:38912
	ds_read_b128 v[220:223], v205 offset:39936
	global_load_lds_dwordx4 v[228:229], off
	s_mov_b32 m0, s47
	v_lshl_add_u64 v[228:229], s[30:31], 0, v[170:171]
	global_load_lds_dwordx4 v[228:229], off
	s_waitcnt vmcnt(8) lgkmcnt(0)
	s_barrier
	s_setprio 1
	v_mfma_f32_16x16x32_bf16 v[128:131], v[132:135], v[164:167], v[128:131]
	v_mfma_f32_16x16x32_bf16 v[124:127], v[140:143], v[164:167], v[124:127]
	v_mfma_f32_16x16x32_bf16 v[112:115], v[132:135], v[186:189], v[112:115]
	v_mfma_f32_16x16x32_bf16 v[108:111], v[140:143], v[186:189], v[108:111]
	v_mfma_f32_16x16x32_bf16 v[96:99], v[132:135], v[208:211], v[96:99]
	v_mfma_f32_16x16x32_bf16 v[92:95], v[140:143], v[208:211], v[92:95]
	v_mfma_f32_16x16x32_bf16 v[80:83], v[132:135], v[216:219], v[80:83]
	v_mfma_f32_16x16x32_bf16 v[76:79], v[140:143], v[216:219], v[76:79]
	v_mfma_f32_16x16x32_bf16 v[128:131], v[136:139], v[182:185], v[128:131]
	v_mfma_f32_16x16x32_bf16 v[124:127], v[144:147], v[182:185], v[124:127]
	v_mfma_f32_16x16x32_bf16 v[112:115], v[136:139], v[190:193], v[112:115]
	v_mfma_f32_16x16x32_bf16 v[108:111], v[144:147], v[190:193], v[108:111]
	v_mfma_f32_16x16x32_bf16 v[96:99], v[136:139], v[212:215], v[96:99]
	v_mfma_f32_16x16x32_bf16 v[92:95], v[144:147], v[212:215], v[92:95]
	v_mfma_f32_16x16x32_bf16 v[80:83], v[136:139], v[220:223], v[80:83]
	v_mfma_f32_16x16x32_bf16 v[76:79], v[144:147], v[220:223], v[76:79]
	s_setprio 0
	s_setprio 1
	v_mfma_f32_16x16x32_bf16 v[120:123], v[148:151], v[164:167], v[120:123]
	v_mfma_f32_16x16x32_bf16 v[116:119], v[156:159], v[164:167], v[116:119]
	v_mfma_f32_16x16x32_bf16 v[104:107], v[148:151], v[186:189], v[104:107]
	v_mfma_f32_16x16x32_bf16 v[100:103], v[156:159], v[186:189], v[100:103]
	v_mfma_f32_16x16x32_bf16 v[88:91], v[148:151], v[208:211], v[88:91]
	v_mfma_f32_16x16x32_bf16 v[84:87], v[156:159], v[208:211], v[84:87]
	v_mfma_f32_16x16x32_bf16 v[72:75], v[148:151], v[216:219], v[72:75]
	v_mfma_f32_16x16x32_bf16 v[68:71], v[156:159], v[216:219], v[68:71]
	v_mfma_f32_16x16x32_bf16 v[120:123], v[152:155], v[182:185], v[120:123]
	v_mfma_f32_16x16x32_bf16 v[116:119], v[160:163], v[182:185], v[116:119]
	v_mfma_f32_16x16x32_bf16 v[104:107], v[152:155], v[190:193], v[104:107]
	v_mfma_f32_16x16x32_bf16 v[100:103], v[160:163], v[190:193], v[100:103]
	v_mfma_f32_16x16x32_bf16 v[88:91], v[152:155], v[212:215], v[88:91]
	v_mfma_f32_16x16x32_bf16 v[84:87], v[160:163], v[212:215], v[84:87]
	v_mfma_f32_16x16x32_bf16 v[72:75], v[152:155], v[220:223], v[72:75]
	v_mfma_f32_16x16x32_bf16 v[68:71], v[160:163], v[220:223], v[68:71]
	s_setprio 0
	s_barrier
; #define PG8_STAGE(bufoff, gbase, voff) do { _Pragma("unroll") for (int _i = 0; _i < 2; ++_i) \
;         __builtin_amdgcn_global_load_lds((const unsigned*)((const char*)(gbase) + (voff)[_i]), (PG8_LAS unsigned*)(lds + (bufoff) + ldsw + _i * 8192), 16, 0, 0); } while (0)
; #define PG8_LDA(dst, b, h) do { _Pragma("unroll") for (int m = 0; m < 4; ++m) _Pragma("unroll") for (int k = 0; k < 2; ++k) dst[m][k] = *(const PG8_LAS bf16x8*)(lds + PG8_SA(b, h) + aoff + m * 2048 + k * 1024); } while (0)
; #define PG8_MMA(ai, bj, At, Bt) do { __builtin_amdgcn_s_setprio(1); _Pragma("unroll") for (int m = 0; m < 4; ++m) _Pragma("unroll") for (int n = 0; n < 2; ++n) _Pragma("unroll") for (int k = 0; k < 2; ++k) \
;         acc[ai][bj][m][n] = __builtin_amdgcn_mfma_f32_16x16x32_bf16(Bt[n][k], At[m][k], acc[ai][bj][m][n], 0, 0, 0); __builtin_amdgcn_s_setprio(0); } while (0)
; #define PG8_WAIT_V(n) asm volatile("s_waitcnt vmcnt(" #n ")" ::: "memory")
; #define PG8_WAIT_L(n) asm volatile("s_waitcnt lgkmcnt(" #n ")" ::: "memory")
; #define PG8_BAR __builtin_amdgcn_s_barrier()
; #define PG8_SCHED __builtin_amdgcn_sched_barrier(0)
; template <class Epi, class Sched, bool ALIGN_EPI = false, bool SP2 = false>
; __device__ __forceinline__ void gemm_phase(PG8_LAS unsigned char* lds, const Gemm g, const Sched& S, const Epi& E) {
;     ...
;         for (int t = 0; t < nt; t += 2) {
;             const bool last = (t == nt - 2);
;             const char* a1 = cA + (size_t)(t + 1) * kstep;
;             const char* a2 = last ? nA : cA + (size_t)(t + 2) * kstep; const char* b2 = last ? nB : cB + (size_t)(t + 2) * kstep;
;     ...
;             PG8_LDA(At, 1, 1); PG8_STAGE(PG8_SB(1, 0), b3, voffB); PG8_STAGE(PG8_SB(1, 1), b3 + hstep, voffB); PG8_STAGE(PG8_SA(1, 0), a3, voffA);
;             PG8_WAIT_V(8); PG8_WAIT_L(0); PG8_BAR; PG8_MMA(1, 0, At, B0); PG8_MMA(1, 1, At, B1); PG8_BAR; PG8_SCHED;
	s_add_i32 s30, s53, s41
	v_lshl_add_u64 v[194:195], v[194:195], 0, s[82:83]
	s_mov_b32 m0, s30
	ds_read_b128 v[164:167], v205 offset:49152
	ds_read_b128 v[182:185], v205 offset:50176
	ds_read_b128 v[186:189], v205 offset:51200
	ds_read_b128 v[190:193], v205 offset:52224
	ds_read_b128 v[208:211], v205 offset:53248
	ds_read_b128 v[212:215], v205 offset:54272
	ds_read_b128 v[216:219], v205 offset:55296
	ds_read_b128 v[220:223], v205 offset:56320
	global_load_lds_dwordx4 v[194:195], off
	s_add_i32 m0, s30, 0x2000
	s_add_u32 s28, s28, 0x40080
	v_lshl_add_u64 v[194:195], v[202:203], 0, s[82:83]
	s_addc_u32 s29, s29, 0
	s_add_i32 s30, s54, s41
	global_load_lds_dwordx4 v[194:195], off
	s_mov_b32 m0, s30
	v_lshl_add_u64 v[194:195], s[28:29], 0, v[168:169]
	global_load_lds_dwordx4 v[194:195], off
	s_add_i32 m0, s30, 0x2000
	v_lshl_add_u64 v[194:195], s[28:29], 0, v[172:173]
	global_load_lds_dwordx4 v[194:195], off
	s_mov_b32 m0, s50
	v_lshl_add_u64 v[194:195], v[224:225], 0, s[82:83]
	global_load_lds_dwordx4 v[194:195], off
	s_mov_b32 m0, s51
	v_lshl_add_u64 v[194:195], v[226:227], 0, s[82:83]
	global_load_lds_dwordx4 v[194:195], off
	s_waitcnt vmcnt(8) lgkmcnt(0)
	s_barrier
	s_setprio 1
	v_mfma_f32_16x16x32_bf16 v[64:67], v[132:135], v[164:167], v[64:67]
	v_mfma_f32_16x16x32_bf16 v[60:63], v[140:143], v[164:167], v[60:63]
	v_mfma_f32_16x16x32_bf16 v[48:51], v[132:135], v[186:189], v[48:51]
	v_mfma_f32_16x16x32_bf16 v[44:47], v[140:143], v[186:189], v[44:47]
	v_mfma_f32_16x16x32_bf16 v[32:35], v[132:135], v[208:211], v[32:35]
	v_mfma_f32_16x16x32_bf16 v[28:31], v[140:143], v[208:211], v[28:31]
	v_mfma_f32_16x16x32_bf16 v[16:19], v[132:135], v[216:219], v[16:19]
	v_mfma_f32_16x16x32_bf16 v[12:15], v[140:143], v[216:219], v[12:15]
	v_mfma_f32_16x16x32_bf16 v[64:67], v[136:139], v[182:185], v[64:67]
	v_mfma_f32_16x16x32_bf16 v[60:63], v[144:147], v[182:185], v[60:63]
	v_mfma_f32_16x16x32_bf16 v[48:51], v[136:139], v[190:193], v[48:51]
	v_mfma_f32_16x16x32_bf16 v[44:47], v[144:147], v[190:193], v[44:47]
	v_mfma_f32_16x16x32_bf16 v[32:35], v[136:139], v[212:215], v[32:35]
	v_mfma_f32_16x16x32_bf16 v[28:31], v[144:147], v[212:215], v[28:31]
	v_mfma_f32_16x16x32_bf16 v[16:19], v[136:139], v[220:223], v[16:19]
	v_mfma_f32_16x16x32_bf16 v[12:15], v[144:147], v[220:223], v[12:15]
	s_setprio 0
	s_setprio 1
	v_mfma_f32_16x16x32_bf16 v[56:59], v[148:151], v[164:167], v[56:59]
	v_mfma_f32_16x16x32_bf16 v[52:55], v[156:159], v[164:167], v[52:55]
	v_mfma_f32_16x16x32_bf16 v[40:43], v[148:151], v[186:189], v[40:43]
	v_mfma_f32_16x16x32_bf16 v[36:39], v[156:159], v[186:189], v[36:39]
	v_mfma_f32_16x16x32_bf16 v[24:27], v[148:151], v[208:211], v[24:27]
	v_mfma_f32_16x16x32_bf16 v[20:23], v[156:159], v[208:211], v[20:23]
	v_mfma_f32_16x16x32_bf16 v[8:11], v[148:151], v[216:219], v[8:11]
	v_mfma_f32_16x16x32_bf16 v[4:7], v[156:159], v[216:219], v[4:7]
	v_mfma_f32_16x16x32_bf16 v[56:59], v[152:155], v[182:185], v[56:59]
	v_mfma_f32_16x16x32_bf16 v[52:55], v[160:163], v[182:185], v[52:55]
	v_mfma_f32_16x16x32_bf16 v[40:43], v[152:155], v[190:193], v[40:43]
	v_mfma_f32_16x16x32_bf16 v[36:39], v[160:163], v[190:193], v[36:39]
	v_mfma_f32_16x16x32_bf16 v[24:27], v[152:155], v[212:215], v[24:27]
	v_mfma_f32_16x16x32_bf16 v[20:23], v[160:163], v[212:215], v[20:23]
	v_mfma_f32_16x16x32_bf16 v[8:11], v[152:155], v[220:223], v[8:11]
	v_mfma_f32_16x16x32_bf16 v[4:7], v[160:163], v[220:223], v[4:7]
	s_setprio 0
	s_barrier
	s_add_i32 s45, s45, 2
	s_add_u32 s8, s8, 0x100
	s_addc_u32 s9, s9, 0
	s_add_u32 s23, s23, 0x100
	s_addc_u32 s44, s44, 0
	s_cmp_gt_u32 s45, 13
	s_cbranch_scc0 .LBB0_100
	s_and_b64 vcc, exec, s[14:15]
	s_cbranch_vccz .LBB0_103
	s_barrier

; #define PG8_STAGE(bufoff, gbase, voff) do { _Pragma("unroll") for (int _i = 0; _i < 2; ++_i) \
;         __builtin_amdgcn_global_load_lds((const unsigned*)((const char*)(gbase) + (voff)[_i]), (PG8_LAS unsigned*)(lds + (bufoff) + ldsw + _i * 8192), 16, 0, 0); } while (0)
; #define PG8_LDA(dst, b, h) do { _Pragma("unroll") for (int m = 0; m < 4; ++m) _Pragma("unroll") for (int k = 0; k < 2; ++k) dst[m][k] = *(const PG8_LAS bf16x8*)(lds + PG8_SA(b, h) + aoff + m * 2048 + k * 1024); } while (0)
; #define PG8_LDB(dst, b, h) do { _Pragma("unroll") for (int n = 0; n < 2; ++n) _Pragma("unroll") for (int k = 0; k < 2; ++k) dst[n][k] = *(const PG8_LAS bf16x8*)(lds + PG8_SB(b, h) + boff + n * 2048 + k * 1024); } while (0)
; #define PG8_MMA(ai, bj, At, Bt) do { __builtin_amdgcn_s_setprio(1); _Pragma("unroll") for (int m = 0; m < 4; ++m) _Pragma("unroll") for (int n = 0; n < 2; ++n) _Pragma("unroll") for (int k = 0; k < 2; ++k) \
;         acc[ai][bj][m][n] = __builtin_amdgcn_mfma_f32_16x16x32_bf16(Bt[n][k], At[m][k], acc[ai][bj][m][n], 0, 0, 0); __builtin_amdgcn_s_setprio(0); } while (0)
; #define PG8_WAIT_V(n) asm volatile("s_waitcnt vmcnt(" #n ")" ::: "memory")
; #define PG8_WAIT_L(n) asm volatile("s_waitcnt lgkmcnt(" #n ")" ::: "memory")
; #define PG8_BAR __builtin_amdgcn_s_barrier()
; #define PG8_SCHED __builtin_amdgcn_sched_barrier(0)
; template <class Epi, class Sched, bool ALIGN_EPI = false, bool SP2 = false>
; __device__ __forceinline__ void gemm_phase(PG8_LAS unsigned char* lds, const Gemm g, const Sched& S, const Epi& E) {
;     ...
;         for (int t = 0; t < nt; t += 2) {
;             const bool last = (t == nt - 2);
;             const char* a1 = cA + (size_t)(t + 1) * kstep;
;             const char* a2 = last ? nA : cA + (size_t)(t + 2) * kstep; const char* b2 = last ? nB : cB + (size_t)(t + 2) * kstep;
;             const char* a3 = a2 + kstep; const char* b3 = b2 + kstep;
;             if (last && has_next) S.a_ready(nxt);
;             if constexpr (SP2) {
;             PG8_LDB(B0, 0, 0); PG8_LDB(B1, 0, 1); PG8_SCHED; PG8_LDA(At, 0, 0); PG8_STAGE(PG8_SA(1, 1), a1 + hstep, voffA);
;             PG8_WAIT_V(8); PG8_WAIT_L(0); PG8_BAR; PG8_MMA(0, 0, At, B0); PG8_MMA(0, 1, At, B1); PG8_BAR; PG8_SCHED;
;             PG8_LDA(At, 0, 1); PG8_STAGE(PG8_SB(0, 0), b2, voffB); PG8_STAGE(PG8_SB(0, 1), b2 + hstep, voffB); PG8_STAGE(PG8_SA(0, 0), a2, voffA);
.LBB0_329:
	s_add_u32 s30, s28, 0xfffc0080
	s_addc_u32 s31, s29, -1
	s_add_i32 s52, 0, 0x10000
	s_cmp_eq_u32 s45, 12
	s_cselect_b32 s35, s3, s31
	s_cselect_b32 s34, s17, s30
	s_cselect_b32 s31, s19, s44
	s_cselect_b32 s30, s25, s27
	s_add_i32 s54, 0, 0x14000
	v_add_u32_e32 v128, s52, v251
	v_add_u32_e32 v156, s54, v251
	ds_read_b128 v[108:111], v128
	ds_read_b128 v[112:115], v128 offset:1024
	ds_read_b128 v[124:127], v128 offset:2048
	ds_read_b128 v[128:131], v128 offset:3072
	ds_read_b128 v[132:135], v156
	ds_read_b128 v[140:143], v156 offset:1024
	ds_read_b128 v[148:151], v156 offset:2048
	ds_read_b128 v[156:159], v156 offset:3072
	v_lshl_add_u64 v[212:213], s[28:29], 0, v[208:209]
	s_add_i32 m0, s42, 0xc000
	ds_read_b128 v[164:167], v253
	ds_read_b128 v[168:171], v253 offset:1024
	ds_read_b128 v[172:175], v253 offset:2048
	ds_read_b128 v[176:179], v253 offset:3072
	ds_read_b128 v[180:183], v253 offset:4096
	ds_read_b128 v[184:187], v253 offset:5120
	ds_read_b128 v[188:191], v253 offset:6144
	ds_read_b128 v[192:195], v253 offset:7168
	global_load_lds_dwordx4 v[212:213], off
	s_add_i32 m0, s42, 0xe000
	v_lshl_add_u64 v[212:213], s[28:29], 0, v[210:211]
	global_load_lds_dwordx4 v[212:213], off
	s_waitcnt vmcnt(8) lgkmcnt(0)
	s_barrier
	s_setprio 1
	v_mfma_f32_16x16x32_bf16 v[160:163], v[108:111], v[164:167], v[160:163]
	v_mfma_f32_16x16x32_bf16 v[152:155], v[124:127], v[164:167], v[152:155]
	v_mfma_f32_16x16x32_bf16 v[120:123], v[108:111], v[172:175], v[120:123]
	v_mfma_f32_16x16x32_bf16 v[116:119], v[124:127], v[172:175], v[116:119]
	v_mfma_f32_16x16x32_bf16 v[96:99], v[108:111], v[180:183], v[96:99]
	v_mfma_f32_16x16x32_bf16 v[92:95], v[124:127], v[180:183], v[92:95]
	v_mfma_f32_16x16x32_bf16 v[80:83], v[108:111], v[188:191], v[80:83]
	v_mfma_f32_16x16x32_bf16 v[76:79], v[124:127], v[188:191], v[76:79]
	v_mfma_f32_16x16x32_bf16 v[160:163], v[112:115], v[168:171], v[160:163]
	v_mfma_f32_16x16x32_bf16 v[152:155], v[128:131], v[168:171], v[152:155]
	v_mfma_f32_16x16x32_bf16 v[120:123], v[112:115], v[176:179], v[120:123]
	v_mfma_f32_16x16x32_bf16 v[116:119], v[128:131], v[176:179], v[116:119]
	v_mfma_f32_16x16x32_bf16 v[96:99], v[112:115], v[184:187], v[96:99]
	v_mfma_f32_16x16x32_bf16 v[92:95], v[128:131], v[184:187], v[92:95]
	v_mfma_f32_16x16x32_bf16 v[80:83], v[112:115], v[192:195], v[80:83]
	v_mfma_f32_16x16x32_bf16 v[76:79], v[128:131], v[192:195], v[76:79]
	s_setprio 0
	s_setprio 1
	v_mfma_f32_16x16x32_bf16 v[144:147], v[132:135], v[164:167], v[144:147]
	v_mfma_f32_16x16x32_bf16 v[136:139], v[148:151], v[164:167], v[136:139]
	v_mfma_f32_16x16x32_bf16 v[104:107], v[132:135], v[172:175], v[104:107]
	v_mfma_f32_16x16x32_bf16 v[100:103], v[148:151], v[172:175], v[100:103]
	v_mfma_f32_16x16x32_bf16 v[88:91], v[132:135], v[180:183], v[88:91]
	v_mfma_f32_16x16x32_bf16 v[84:87], v[148:151], v[180:183], v[84:87]
	v_mfma_f32_16x16x32_bf16 v[72:75], v[132:135], v[188:191], v[72:75]
	v_mfma_f32_16x16x32_bf16 v[68:71], v[148:151], v[188:191], v[68:71]
	v_mfma_f32_16x16x32_bf16 v[144:147], v[140:143], v[168:171], v[144:147]
	v_mfma_f32_16x16x32_bf16 v[136:139], v[156:159], v[168:171], v[136:139]
	v_mfma_f32_16x16x32_bf16 v[104:107], v[140:143], v[176:179], v[104:107]
	v_mfma_f32_16x16x32_bf16 v[100:103], v[156:159], v[176:179], v[100:103]
	v_mfma_f32_16x16x32_bf16 v[88:91], v[140:143], v[184:187], v[88:91]
	v_mfma_f32_16x16x32_bf16 v[84:87], v[156:159], v[184:187], v[84:87]
	v_mfma_f32_16x16x32_bf16 v[72:75], v[140:143], v[192:195], v[72:75]
	v_mfma_f32_16x16x32_bf16 v[68:71], v[156:159], v[192:195], v[68:71]
	s_setprio 0
	s_barrier
	s_add_i32 s52, s52, s41
	v_lshl_add_u64 v[212:213], s[30:31], 0, v[202:203]
	s_mov_b32 m0, s52
	ds_read_b128 v[164:167], v253 offset:16384
	ds_read_b128 v[168:171], v253 offset:17408
	ds_read_b128 v[172:175], v253 offset:18432
	ds_read_b128 v[176:179], v253 offset:19456
	ds_read_b128 v[180:183], v253 offset:20480
	ds_read_b128 v[184:187], v253 offset:21504
	ds_read_b128 v[188:191], v253 offset:22528
	ds_read_b128 v[192:195], v253 offset:23552
	global_load_lds_dwordx4 v[212:213], off
	s_add_i32 m0, s52, 0x2000
	s_add_u32 s52, s30, 0x40000
	v_lshl_add_u64 v[214:215], s[30:31], 0, v[206:207]
	s_addc_u32 s53, s31, 0
	s_add_i32 s54, s54, s41
	global_load_lds_dwordx4 v[214:215], off
	v_lshl_add_u64 v[216:217], s[52:53], 0, v[202:203]
	s_mov_b32 m0, s54
	v_lshl_add_u64 v[218:219], s[34:35], 0, v[204:205]
	global_load_lds_dwordx4 v[216:217], off
	s_add_i32 m0, s54, 0x2000
	v_lshl_add_u64 v[216:217], s[52:53], 0, v[206:207]
	global_load_lds_dwordx4 v[216:217], off
	s_mov_b32 m0, s42
	v_lshl_add_u64 v[216:217], s[34:35], 0, v[0:1]
	global_load_lds_dwordx4 v[216:217], off
	s_mov_b32 m0, s43
	s_add_i32 s52, 0, 0x18000
	global_load_lds_dwordx4 v[218:219], off
	s_waitcnt vmcnt(8) lgkmcnt(0)
	s_barrier
; #define PG8_STAGE(bufoff, gbase, voff) do { _Pragma("unroll") for (int _i = 0; _i < 2; ++_i) \
;         __builtin_amdgcn_global_load_lds((const unsigned*)((const char*)(gbase) + (voff)[_i]), (PG8_LAS unsigned*)(lds + (bufoff) + ldsw + _i * 8192), 16, 0, 0); } while (0)
; #define PG8_LDA(dst, b, h) do { _Pragma("unroll") for (int m = 0; m < 4; ++m) _Pragma("unroll") for (int k = 0; k < 2; ++k) dst[m][k] = *(const PG8_LAS bf16x8*)(lds + PG8_SA(b, h) + aoff + m * 2048 + k * 1024); } while (0)
; #define PG8_LDB(dst, b, h) do { _Pragma("unroll") for (int n = 0; n < 2; ++n) _Pragma("unroll") for (int k = 0; k < 2; ++k) dst[n][k] = *(const PG8_LAS bf16x8*)(lds + PG8_SB(b, h) + boff + n * 2048 + k * 1024); } while (0)
; #define PG8_MMA(ai, bj, At, Bt) do { __builtin_amdgcn_s_setprio(1); _Pragma("unroll") for (int m = 0; m < 4; ++m) _Pragma("unroll") for (int n = 0; n < 2; ++n) _Pragma("unroll") for (int k = 0; k < 2; ++k) \
;         acc[ai][bj][m][n] = __builtin_amdgcn_mfma_f32_16x16x32_bf16(Bt[n][k], At[m][k], acc[ai][bj][m][n], 0, 0, 0); __builtin_amdgcn_s_setprio(0); } while (0)
; #define PG8_WAIT_V(n) asm volatile("s_waitcnt vmcnt(" #n ")" ::: "memory")
; #define PG8_WAIT_L(n) asm volatile("s_waitcnt lgkmcnt(" #n ")" ::: "memory")
; #define PG8_BAR __builtin_amdgcn_s_barrier()
; #define PG8_SCHED __builtin_amdgcn_sched_barrier(0)
; template <class Epi, class Sched, bool ALIGN_EPI = false, bool SP2 = false>
; __device__ __forceinline__ void gemm_phase(PG8_LAS unsigned char* lds, const Gemm g, const Sched& S, const Epi& E) {
;     ...
;             PG8_WAIT_V(8); PG8_WAIT_L(0); PG8_BAR; PG8_MMA(1, 0, At, B0); PG8_MMA(1, 1, At, B1); PG8_BAR; PG8_SCHED;
;             PG8_LDB(B0, 1, 0); PG8_LDB(B1, 1, 1); PG8_SCHED; PG8_LDA(At, 1, 0); PG8_STAGE(PG8_SA(0, 1), a2 + hstep, voffA);
;             PG8_WAIT_V(8); PG8_WAIT_L(0); PG8_BAR; PG8_MMA(0, 0, At, B0); PG8_MMA(0, 1, At, B1); PG8_BAR; PG8_SCHED;
	s_setprio 1
	v_mfma_f32_16x16x32_bf16 v[64:67], v[108:111], v[164:167], v[64:67]
	v_mfma_f32_16x16x32_bf16 v[60:63], v[124:127], v[164:167], v[60:63]
	v_mfma_f32_16x16x32_bf16 v[48:51], v[108:111], v[172:175], v[48:51]
	v_mfma_f32_16x16x32_bf16 v[44:47], v[124:127], v[172:175], v[44:47]
	v_mfma_f32_16x16x32_bf16 v[32:35], v[108:111], v[180:183], v[32:35]
	v_mfma_f32_16x16x32_bf16 v[28:31], v[124:127], v[180:183], v[28:31]
	v_mfma_f32_16x16x32_bf16 v[16:19], v[108:111], v[188:191], v[16:19]
	v_mfma_f32_16x16x32_bf16 v[12:15], v[124:127], v[188:191], v[12:15]
	v_mfma_f32_16x16x32_bf16 v[64:67], v[112:115], v[168:171], v[64:67]
	v_mfma_f32_16x16x32_bf16 v[60:63], v[128:131], v[168:171], v[60:63]
	v_mfma_f32_16x16x32_bf16 v[48:51], v[112:115], v[176:179], v[48:51]
	v_mfma_f32_16x16x32_bf16 v[44:47], v[128:131], v[176:179], v[44:47]
	v_mfma_f32_16x16x32_bf16 v[32:35], v[112:115], v[184:187], v[32:35]
	v_mfma_f32_16x16x32_bf16 v[28:31], v[128:131], v[184:187], v[28:31]
	v_mfma_f32_16x16x32_bf16 v[16:19], v[112:115], v[192:195], v[16:19]
	v_mfma_f32_16x16x32_bf16 v[12:15], v[128:131], v[192:195], v[12:15]
	s_setprio 0
	s_setprio 1
	v_mfma_f32_16x16x32_bf16 v[56:59], v[132:135], v[164:167], v[56:59]
	v_mfma_f32_16x16x32_bf16 v[52:55], v[148:151], v[164:167], v[52:55]
	v_mfma_f32_16x16x32_bf16 v[40:43], v[132:135], v[172:175], v[40:43]
	v_mfma_f32_16x16x32_bf16 v[36:39], v[148:151], v[172:175], v[36:39]
	v_mfma_f32_16x16x32_bf16 v[24:27], v[132:135], v[180:183], v[24:27]
	v_mfma_f32_16x16x32_bf16 v[20:23], v[148:151], v[180:183], v[20:23]
	v_mfma_f32_16x16x32_bf16 v[8:11], v[132:135], v[188:191], v[8:11]
	v_mfma_f32_16x16x32_bf16 v[4:7], v[148:151], v[188:191], v[4:7]
	v_mfma_f32_16x16x32_bf16 v[56:59], v[140:143], v[168:171], v[56:59]
	v_mfma_f32_16x16x32_bf16 v[52:55], v[156:159], v[168:171], v[52:55]
	v_mfma_f32_16x16x32_bf16 v[40:43], v[140:143], v[176:179], v[40:43]
	v_mfma_f32_16x16x32_bf16 v[36:39], v[156:159], v[176:179], v[36:39]
	v_mfma_f32_16x16x32_bf16 v[24:27], v[140:143], v[184:187], v[24:27]
	v_mfma_f32_16x16x32_bf16 v[20:23], v[156:159], v[184:187], v[20:23]
	v_mfma_f32_16x16x32_bf16 v[8:11], v[140:143], v[192:195], v[8:11]
	v_mfma_f32_16x16x32_bf16 v[4:7], v[156:159], v[192:195], v[4:7]
	s_setprio 0
	s_barrier
	s_add_i32 s53, 0, 0x1c000
	v_add_u32_e32 v128, s52, v251
	v_add_u32_e32 v156, s53, v251
	ds_read_b128 v[108:111], v128
	ds_read_b128 v[112:115], v128 offset:1024
	ds_read_b128 v[124:127], v128 offset:2048
	ds_read_b128 v[128:131], v128 offset:3072
	ds_read_b128 v[132:135], v156
	ds_read_b128 v[140:143], v156 offset:1024
	ds_read_b128 v[148:151], v156 offset:2048
	ds_read_b128 v[156:159], v156 offset:3072
	s_add_u32 s34, s34, 0x40000
	s_addc_u32 s35, s35, 0
	s_mov_b32 m0, s46
	v_lshl_add_u64 v[220:221], s[34:35], 0, v[0:1]
	ds_read_b128 v[164:167], v253 offset:32768
	ds_read_b128 v[168:171], v253 offset:33792
	ds_read_b128 v[172:175], v253 offset:34816
	ds_read_b128 v[176:179], v253 offset:35840
	ds_read_b128 v[180:183], v253 offset:36864
	ds_read_b128 v[184:187], v253 offset:37888
	ds_read_b128 v[188:191], v253 offset:38912
	ds_read_b128 v[192:195], v253 offset:39936
	global_load_lds_dwordx4 v[220:221], off
	s_mov_b32 m0, s47
	v_lshl_add_u64 v[220:221], s[34:35], 0, v[204:205]
	global_load_lds_dwordx4 v[220:221], off
	s_waitcnt vmcnt(8) lgkmcnt(0)
	s_barrier
	s_setprio 1
	v_mfma_f32_16x16x32_bf16 v[160:163], v[108:111], v[164:167], v[160:163]
	v_mfma_f32_16x16x32_bf16 v[152:155], v[124:127], v[164:167], v[152:155]
	v_mfma_f32_16x16x32_bf16 v[120:123], v[108:111], v[172:175], v[120:123]
	v_mfma_f32_16x16x32_bf16 v[116:119], v[124:127], v[172:175], v[116:119]
	v_mfma_f32_16x16x32_bf16 v[96:99], v[108:111], v[180:183], v[96:99]
	v_mfma_f32_16x16x32_bf16 v[92:95], v[124:127], v[180:183], v[92:95]
	v_mfma_f32_16x16x32_bf16 v[80:83], v[108:111], v[188:191], v[80:83]
	v_mfma_f32_16x16x32_bf16 v[76:79], v[124:127], v[188:191], v[76:79]
	v_mfma_f32_16x16x32_bf16 v[160:163], v[112:115], v[168:171], v[160:163]
	v_mfma_f32_16x16x32_bf16 v[152:155], v[128:131], v[168:171], v[152:155]
	v_mfma_f32_16x16x32_bf16 v[120:123], v[112:115], v[176:179], v[120:123]
	v_mfma_f32_16x16x32_bf16 v[116:119], v[128:131], v[176:179], v[116:119]
	v_mfma_f32_16x16x32_bf16 v[96:99], v[112:115], v[184:187], v[96:99]
	v_mfma_f32_16x16x32_bf16 v[92:95], v[128:131], v[184:187], v[92:95]
	v_mfma_f32_16x16x32_bf16 v[80:83], v[112:115], v[192:195], v[80:83]
	v_mfma_f32_16x16x32_bf16 v[76:79], v[128:131], v[192:195], v[76:79]
	s_setprio 0
	s_setprio 1
	v_mfma_f32_16x16x32_bf16 v[144:147], v[132:135], v[164:167], v[144:147]
	v_mfma_f32_16x16x32_bf16 v[136:139], v[148:151], v[164:167], v[136:139]
	v_mfma_f32_16x16x32_bf16 v[104:107], v[132:135], v[172:175], v[104:107]
	v_mfma_f32_16x16x32_bf16 v[100:103], v[148:151], v[172:175], v[100:103]
	v_mfma_f32_16x16x32_bf16 v[88:91], v[132:135], v[180:183], v[88:91]
	v_mfma_f32_16x16x32_bf16 v[84:87], v[148:151], v[180:183], v[84:87]
	v_mfma_f32_16x16x32_bf16 v[72:75], v[132:135], v[188:191], v[72:75]
	v_mfma_f32_16x16x32_bf16 v[68:71], v[148:151], v[188:191], v[68:71]
	v_mfma_f32_16x16x32_bf16 v[144:147], v[140:143], v[168:171], v[144:147]
	v_mfma_f32_16x16x32_bf16 v[136:139], v[156:159], v[168:171], v[136:139]
	v_mfma_f32_16x16x32_bf16 v[104:107], v[140:143], v[176:179], v[104:107]
	v_mfma_f32_16x16x32_bf16 v[100:103], v[156:159], v[176:179], v[100:103]
	v_mfma_f32_16x16x32_bf16 v[88:91], v[140:143], v[184:187], v[88:91]
	v_mfma_f32_16x16x32_bf16 v[84:87], v[156:159], v[184:187], v[84:87]
	v_mfma_f32_16x16x32_bf16 v[72:75], v[140:143], v[192:195], v[72:75]
	v_mfma_f32_16x16x32_bf16 v[68:71], v[156:159], v[192:195], v[68:71]
	s_setprio 0
	s_barrier
; #define PG8_STAGE(bufoff, gbase, voff) do { _Pragma("unroll") for (int _i = 0; _i < 2; ++_i) \
;         __builtin_amdgcn_global_load_lds((const unsigned*)((const char*)(gbase) + (voff)[_i]), (PG8_LAS unsigned*)(lds + (bufoff) + ldsw + _i * 8192), 16, 0, 0); } while (0)
; #define PG8_LDA(dst, b, h) do { _Pragma("unroll") for (int m = 0; m < 4; ++m) _Pragma("unroll") for (int k = 0; k < 2; ++k) dst[m][k] = *(const PG8_LAS bf16x8*)(lds + PG8_SA(b, h) + aoff + m * 2048 + k * 1024); } while (0)
; #define PG8_MMA(ai, bj, At, Bt) do { __builtin_amdgcn_s_setprio(1); _Pragma("unroll") for (int m = 0; m < 4; ++m) _Pragma("unroll") for (int n = 0; n < 2; ++n) _Pragma("unroll") for (int k = 0; k < 2; ++k) \
;         acc[ai][bj][m][n] = __builtin_amdgcn_mfma_f32_16x16x32_bf16(Bt[n][k], At[m][k], acc[ai][bj][m][n], 0, 0, 0); __builtin_amdgcn_s_setprio(0); } while (0)
; #define PG8_WAIT_V(n) asm volatile("s_waitcnt vmcnt(" #n ")" ::: "memory")
; #define PG8_WAIT_L(n) asm volatile("s_waitcnt lgkmcnt(" #n ")" ::: "memory")
; #define PG8_BAR __builtin_amdgcn_s_barrier()
; #define PG8_SCHED __builtin_amdgcn_sched_barrier(0)
; template <class Epi, class Sched, bool ALIGN_EPI = false, bool SP2 = false>
; __device__ __forceinline__ void gemm_phase(PG8_LAS unsigned char* lds, const Gemm g, const Sched& S, const Epi& E) {
;     ...
;         for (int t = 0; t < nt; t += 2) {
;             const bool last = (t == nt - 2);
;             const char* a1 = cA + (size_t)(t + 1) * kstep;
;             const char* a2 = last ? nA : cA + (size_t)(t + 2) * kstep; const char* b2 = last ? nB : cB + (size_t)(t + 2) * kstep;
;     ...
;             PG8_LDA(At, 1, 1); PG8_STAGE(PG8_SB(1, 0), b3, voffB); PG8_STAGE(PG8_SB(1, 1), b3 + hstep, voffB); PG8_STAGE(PG8_SA(1, 0), a3, voffA);
;             PG8_WAIT_V(8); PG8_WAIT_L(0); PG8_BAR; PG8_MMA(1, 0, At, B0); PG8_MMA(1, 1, At, B1); PG8_BAR; PG8_SCHED;
	s_add_i32 s34, s52, s41
	v_lshl_add_u64 v[212:213], v[212:213], 0, s[82:83]
	s_mov_b32 m0, s34
	ds_read_b128 v[164:167], v253 offset:49152
	ds_read_b128 v[168:171], v253 offset:50176
	ds_read_b128 v[172:175], v253 offset:51200
	ds_read_b128 v[176:179], v253 offset:52224
	ds_read_b128 v[180:183], v253 offset:53248
	ds_read_b128 v[184:187], v253 offset:54272
	ds_read_b128 v[188:191], v253 offset:55296
	ds_read_b128 v[192:195], v253 offset:56320
	global_load_lds_dwordx4 v[212:213], off
	s_add_i32 m0, s34, 0x2000
	s_add_u32 s30, s30, 0x40080
	v_lshl_add_u64 v[212:213], v[214:215], 0, s[82:83]
	s_addc_u32 s31, s31, 0
	s_add_i32 s34, s53, s41
	global_load_lds_dwordx4 v[212:213], off
	s_mov_b32 m0, s34
	v_lshl_add_u64 v[212:213], s[30:31], 0, v[202:203]
	global_load_lds_dwordx4 v[212:213], off
	s_add_i32 m0, s34, 0x2000
	v_lshl_add_u64 v[212:213], s[30:31], 0, v[206:207]
	global_load_lds_dwordx4 v[212:213], off
	s_mov_b32 m0, s49
	v_lshl_add_u64 v[212:213], v[216:217], 0, s[82:83]
	global_load_lds_dwordx4 v[212:213], off
	s_mov_b32 m0, s50
	v_lshl_add_u64 v[212:213], v[218:219], 0, s[82:83]
	global_load_lds_dwordx4 v[212:213], off
	s_waitcnt vmcnt(8) lgkmcnt(0)
	s_barrier
	s_setprio 1
	v_mfma_f32_16x16x32_bf16 v[64:67], v[108:111], v[164:167], v[64:67]
	v_mfma_f32_16x16x32_bf16 v[60:63], v[124:127], v[164:167], v[60:63]
	v_mfma_f32_16x16x32_bf16 v[48:51], v[108:111], v[172:175], v[48:51]
	v_mfma_f32_16x16x32_bf16 v[44:47], v[124:127], v[172:175], v[44:47]
	v_mfma_f32_16x16x32_bf16 v[32:35], v[108:111], v[180:183], v[32:35]
	v_mfma_f32_16x16x32_bf16 v[28:31], v[124:127], v[180:183], v[28:31]
	v_mfma_f32_16x16x32_bf16 v[16:19], v[108:111], v[188:191], v[16:19]
	v_mfma_f32_16x16x32_bf16 v[12:15], v[124:127], v[188:191], v[12:15]
	v_mfma_f32_16x16x32_bf16 v[64:67], v[112:115], v[168:171], v[64:67]
	v_mfma_f32_16x16x32_bf16 v[60:63], v[128:131], v[168:171], v[60:63]
	v_mfma_f32_16x16x32_bf16 v[48:51], v[112:115], v[176:179], v[48:51]
	v_mfma_f32_16x16x32_bf16 v[44:47], v[128:131], v[176:179], v[44:47]
	v_mfma_f32_16x16x32_bf16 v[32:35], v[112:115], v[184:187], v[32:35]
	v_mfma_f32_16x16x32_bf16 v[28:31], v[128:131], v[184:187], v[28:31]
	v_mfma_f32_16x16x32_bf16 v[16:19], v[112:115], v[192:195], v[16:19]
	v_mfma_f32_16x16x32_bf16 v[12:15], v[128:131], v[192:195], v[12:15]
	s_setprio 0
	s_setprio 1
	v_mfma_f32_16x16x32_bf16 v[56:59], v[132:135], v[164:167], v[56:59]
	v_mfma_f32_16x16x32_bf16 v[52:55], v[148:151], v[164:167], v[52:55]
	v_mfma_f32_16x16x32_bf16 v[40:43], v[132:135], v[172:175], v[40:43]
	v_mfma_f32_16x16x32_bf16 v[36:39], v[148:151], v[172:175], v[36:39]
	v_mfma_f32_16x16x32_bf16 v[24:27], v[132:135], v[180:183], v[24:27]
	v_mfma_f32_16x16x32_bf16 v[20:23], v[148:151], v[180:183], v[20:23]
	v_mfma_f32_16x16x32_bf16 v[8:11], v[132:135], v[188:191], v[8:11]
	v_mfma_f32_16x16x32_bf16 v[4:7], v[148:151], v[188:191], v[4:7]
	v_mfma_f32_16x16x32_bf16 v[56:59], v[140:143], v[168:171], v[56:59]
	v_mfma_f32_16x16x32_bf16 v[52:55], v[156:159], v[168:171], v[52:55]
	v_mfma_f32_16x16x32_bf16 v[40:43], v[140:143], v[176:179], v[40:43]
	v_mfma_f32_16x16x32_bf16 v[36:39], v[156:159], v[176:179], v[36:39]
	v_mfma_f32_16x16x32_bf16 v[24:27], v[140:143], v[184:187], v[24:27]
	v_mfma_f32_16x16x32_bf16 v[20:23], v[156:159], v[184:187], v[20:23]
	v_mfma_f32_16x16x32_bf16 v[8:11], v[140:143], v[192:195], v[8:11]
	v_mfma_f32_16x16x32_bf16 v[4:7], v[156:159], v[192:195], v[4:7]
	s_setprio 0
	s_barrier
	s_add_i32 s45, s45, 2
	s_add_u32 s28, s28, 0x100
	s_addc_u32 s29, s29, 0
	s_add_u32 s27, s27, 0x100
	s_addc_u32 s44, s44, 0
	s_cmp_gt_u32 s45, 13
	s_cbranch_scc0 .LBB0_329
	s_and_b64 vcc, exec, s[14:15]
	s_cbranch_vccz .LBB0_332
	s_barrier

; #define PG8_STAGE(bufoff, gbase, voff) do { _Pragma("unroll") for (int _i = 0; _i < 2; ++_i) \
;         __builtin_amdgcn_global_load_lds((const unsigned*)((const char*)(gbase) + (voff)[_i]), (PG8_LAS unsigned*)(lds + (bufoff) + ldsw + _i * 8192), 16, 0, 0); } while (0)
; #define PG8_LDA(dst, b, h) do { _Pragma("unroll") for (int m = 0; m < 4; ++m) _Pragma("unroll") for (int k = 0; k < 2; ++k) dst[m][k] = *(const PG8_LAS bf16x8*)(lds + PG8_SA(b, h) + aoff + m * 2048 + k * 1024); } while (0)
; #define PG8_LDB(dst, b, h) do { _Pragma("unroll") for (int n = 0; n < 2; ++n) _Pragma("unroll") for (int k = 0; k < 2; ++k) dst[n][k] = *(const PG8_LAS bf16x8*)(lds + PG8_SB(b, h) + boff + n * 2048 + k * 1024); } while (0)
; #define PG8_MMA(ai, bj, At, Bt) do { __builtin_amdgcn_s_setprio(1); _Pragma("unroll") for (int m = 0; m < 4; ++m) _Pragma("unroll") for (int n = 0; n < 2; ++n) _Pragma("unroll") for (int k = 0; k < 2; ++k) \
;         acc[ai][bj][m][n] = __builtin_amdgcn_mfma_f32_16x16x32_bf16(Bt[n][k], At[m][k], acc[ai][bj][m][n], 0, 0, 0); __builtin_amdgcn_s_setprio(0); } while (0)
; #define PG8_WAIT_V(n) asm volatile("s_waitcnt vmcnt(" #n ")" ::: "memory")
; #define PG8_WAIT_L(n) asm volatile("s_waitcnt lgkmcnt(" #n ")" ::: "memory")
; #define PG8_BAR __builtin_amdgcn_s_barrier()
; #define PG8_SCHED __builtin_amdgcn_sched_barrier(0)
; template <class Epi, class Sched, bool ALIGN_EPI = false, bool SP2 = false>
; __device__ __forceinline__ void gemm_phase(PG8_LAS unsigned char* lds, const Gemm g, const Sched& S, const Epi& E) {
;     ...
;         for (int t = 0; t < nt; t += 2) {
;             const bool last = (t == nt - 2);
;             const char* a1 = cA + (size_t)(t + 1) * kstep;
;             const char* a2 = last ? nA : cA + (size_t)(t + 2) * kstep; const char* b2 = last ? nB : cB + (size_t)(t + 2) * kstep;
;             const char* a3 = a2 + kstep; const char* b3 = b2 + kstep;
;             if (last && has_next) S.a_ready(nxt);
;             if constexpr (SP2) {
;             PG8_LDB(B0, 0, 0); PG8_LDB(B1, 0, 1); PG8_SCHED; PG8_LDA(At, 0, 0); PG8_STAGE(PG8_SA(1, 1), a1 + hstep, voffA);
;             PG8_WAIT_V(8); PG8_WAIT_L(0); PG8_BAR; PG8_MMA(0, 0, At, B0); PG8_MMA(0, 1, At, B1); PG8_BAR; PG8_SCHED;
;             PG8_LDA(At, 0, 1); PG8_STAGE(PG8_SB(0, 0), b2, voffB); PG8_STAGE(PG8_SB(0, 1), b2 + hstep, voffB); PG8_STAGE(PG8_SA(0, 0), a2, voffA);
.LBB0_405:
	s_add_u32 s24, s8, 0xfffc0080
	s_addc_u32 s25, s9, -1
	s_add_i32 s47, 0, 0x10000
	s_cmp_eq_u32 s46, 12
	s_cselect_b32 s27, s7, s25
	s_cselect_b32 s26, s17, s24
	s_cselect_b32 s25, s19, s45
	s_cselect_b32 s24, s43, s44
	s_add_i32 s50, 0, 0x14000
	v_add_u32_e32 v156, s47, v164
	v_add_u32_e32 v167, s50, v164
	ds_read_b128 v[144:147], v156
	ds_read_b128 v[148:151], v156 offset:1024
	ds_read_b128 v[152:155], v156 offset:2048
	ds_read_b128 v[156:159], v156 offset:3072
	ds_read_b128 v[160:163], v167
	ds_read_b128 v[168:171], v167 offset:1024
	ds_read_b128 v[172:175], v167 offset:2048
	ds_read_b128 v[176:179], v167 offset:3072
	v_lshl_add_u64 v[198:199], s[8:9], 0, v[140:141]
	s_add_i32 m0, s37, 0xc000
	ds_read_b128 v[180:183], v166
	ds_read_b128 v[184:187], v166 offset:1024
	ds_read_b128 v[188:191], v166 offset:2048
	ds_read_b128 v[192:195], v166 offset:3072
	ds_read_b128 v[202:205], v166 offset:4096
	ds_read_b128 v[206:209], v166 offset:5120
	ds_read_b128 v[210:213], v166 offset:6144
	ds_read_b128 v[214:217], v166 offset:7168
	global_load_lds_dwordx4 v[198:199], off
	s_add_i32 m0, s37, 0xe000
	v_lshl_add_u64 v[198:199], s[8:9], 0, v[142:143]
	global_load_lds_dwordx4 v[198:199], off
	s_waitcnt vmcnt(8) lgkmcnt(0)
	s_barrier
	s_setprio 1
	v_mfma_f32_16x16x32_bf16 v[128:131], v[144:147], v[180:183], v[128:131]
	v_mfma_f32_16x16x32_bf16 v[120:123], v[152:155], v[180:183], v[120:123]
	v_mfma_f32_16x16x32_bf16 v[112:115], v[144:147], v[188:191], v[112:115]
	v_mfma_f32_16x16x32_bf16 v[104:107], v[152:155], v[188:191], v[104:107]
	v_mfma_f32_16x16x32_bf16 v[96:99], v[144:147], v[202:205], v[96:99]
	v_mfma_f32_16x16x32_bf16 v[88:91], v[152:155], v[202:205], v[88:91]
	v_mfma_f32_16x16x32_bf16 v[80:83], v[144:147], v[210:213], v[80:83]
	v_mfma_f32_16x16x32_bf16 v[72:75], v[152:155], v[210:213], v[72:75]
	v_mfma_f32_16x16x32_bf16 v[128:131], v[148:151], v[184:187], v[128:131]
	v_mfma_f32_16x16x32_bf16 v[120:123], v[156:159], v[184:187], v[120:123]
	v_mfma_f32_16x16x32_bf16 v[112:115], v[148:151], v[192:195], v[112:115]
	v_mfma_f32_16x16x32_bf16 v[104:107], v[156:159], v[192:195], v[104:107]
	v_mfma_f32_16x16x32_bf16 v[96:99], v[148:151], v[206:209], v[96:99]
	v_mfma_f32_16x16x32_bf16 v[88:91], v[156:159], v[206:209], v[88:91]
	v_mfma_f32_16x16x32_bf16 v[80:83], v[148:151], v[214:217], v[80:83]
	v_mfma_f32_16x16x32_bf16 v[72:75], v[156:159], v[214:217], v[72:75]
	s_setprio 0
	s_setprio 1
	v_mfma_f32_16x16x32_bf16 v[124:127], v[160:163], v[180:183], v[124:127]
	v_mfma_f32_16x16x32_bf16 v[116:119], v[172:175], v[180:183], v[116:119]
	v_mfma_f32_16x16x32_bf16 v[108:111], v[160:163], v[188:191], v[108:111]
	v_mfma_f32_16x16x32_bf16 v[100:103], v[172:175], v[188:191], v[100:103]
	v_mfma_f32_16x16x32_bf16 v[92:95], v[160:163], v[202:205], v[92:95]
	v_mfma_f32_16x16x32_bf16 v[84:87], v[172:175], v[202:205], v[84:87]
	v_mfma_f32_16x16x32_bf16 v[76:79], v[160:163], v[210:213], v[76:79]
	v_mfma_f32_16x16x32_bf16 v[68:71], v[172:175], v[210:213], v[68:71]
	v_mfma_f32_16x16x32_bf16 v[124:127], v[168:171], v[184:187], v[124:127]
	v_mfma_f32_16x16x32_bf16 v[116:119], v[176:179], v[184:187], v[116:119]
	v_mfma_f32_16x16x32_bf16 v[108:111], v[168:171], v[192:195], v[108:111]
	v_mfma_f32_16x16x32_bf16 v[100:103], v[176:179], v[192:195], v[100:103]
	v_mfma_f32_16x16x32_bf16 v[92:95], v[168:171], v[206:209], v[92:95]
	v_mfma_f32_16x16x32_bf16 v[84:87], v[176:179], v[206:209], v[84:87]
	v_mfma_f32_16x16x32_bf16 v[76:79], v[168:171], v[214:217], v[76:79]
	v_mfma_f32_16x16x32_bf16 v[68:71], v[176:179], v[214:217], v[68:71]
	s_setprio 0
	s_barrier
	s_add_i32 s47, s47, s35
	v_lshl_add_u64 v[198:199], s[24:25], 0, v[134:135]
	s_mov_b32 m0, s47
	ds_read_b128 v[180:183], v166 offset:16384
	ds_read_b128 v[184:187], v166 offset:17408
	ds_read_b128 v[188:191], v166 offset:18432
	ds_read_b128 v[192:195], v166 offset:19456
	ds_read_b128 v[202:205], v166 offset:20480
	ds_read_b128 v[206:209], v166 offset:21504
	ds_read_b128 v[210:213], v166 offset:22528
	ds_read_b128 v[214:217], v166 offset:23552
	global_load_lds_dwordx4 v[198:199], off
	s_add_i32 m0, s47, 0x2000
	s_add_u32 s48, s24, 0x40000
	v_lshl_add_u64 v[218:219], s[24:25], 0, v[0:1]
	s_addc_u32 s49, s25, 0
	s_add_i32 s47, s50, s35
	global_load_lds_dwordx4 v[218:219], off
	v_lshl_add_u64 v[220:221], s[48:49], 0, v[134:135]
	s_mov_b32 m0, s47
	v_lshl_add_u64 v[222:223], s[26:27], 0, v[132:133]
	global_load_lds_dwordx4 v[220:221], off
	s_add_i32 m0, s47, 0x2000
	v_lshl_add_u64 v[220:221], s[48:49], 0, v[0:1]
	global_load_lds_dwordx4 v[220:221], off
	s_mov_b32 m0, s37
	v_lshl_add_u64 v[220:221], s[26:27], 0, v[136:137]
	global_load_lds_dwordx4 v[220:221], off
	s_mov_b32 m0, s38
	s_add_i32 s47, 0, 0x18000
	global_load_lds_dwordx4 v[222:223], off
	s_waitcnt vmcnt(8) lgkmcnt(0)
	s_barrier
; #define PG8_STAGE(bufoff, gbase, voff) do { _Pragma("unroll") for (int _i = 0; _i < 2; ++_i) \
;         __builtin_amdgcn_global_load_lds((const unsigned*)((const char*)(gbase) + (voff)[_i]), (PG8_LAS unsigned*)(lds + (bufoff) + ldsw + _i * 8192), 16, 0, 0); } while (0)
; #define PG8_LDA(dst, b, h) do { _Pragma("unroll") for (int m = 0; m < 4; ++m) _Pragma("unroll") for (int k = 0; k < 2; ++k) dst[m][k] = *(const PG8_LAS bf16x8*)(lds + PG8_SA(b, h) + aoff + m * 2048 + k * 1024); } while (0)
; #define PG8_LDB(dst, b, h) do { _Pragma("unroll") for (int n = 0; n < 2; ++n) _Pragma("unroll") for (int k = 0; k < 2; ++k) dst[n][k] = *(const PG8_LAS bf16x8*)(lds + PG8_SB(b, h) + boff + n * 2048 + k * 1024); } while (0)
; #define PG8_MMA(ai, bj, At, Bt) do { __builtin_amdgcn_s_setprio(1); _Pragma("unroll") for (int m = 0; m < 4; ++m) _Pragma("unroll") for (int n = 0; n < 2; ++n) _Pragma("unroll") for (int k = 0; k < 2; ++k) \
;         acc[ai][bj][m][n] = __builtin_amdgcn_mfma_f32_16x16x32_bf16(Bt[n][k], At[m][k], acc[ai][bj][m][n], 0, 0, 0); __builtin_amdgcn_s_setprio(0); } while (0)
; #define PG8_WAIT_V(n) asm volatile("s_waitcnt vmcnt(" #n ")" ::: "memory")
; #define PG8_WAIT_L(n) asm volatile("s_waitcnt lgkmcnt(" #n ")" ::: "memory")
; #define PG8_BAR __builtin_amdgcn_s_barrier()
; #define PG8_SCHED __builtin_amdgcn_sched_barrier(0)
; template <class Epi, class Sched, bool ALIGN_EPI = false, bool SP2 = false>
; __device__ __forceinline__ void gemm_phase(PG8_LAS unsigned char* lds, const Gemm g, const Sched& S, const Epi& E) {
;     ...
;             PG8_WAIT_V(8); PG8_WAIT_L(0); PG8_BAR; PG8_MMA(1, 0, At, B0); PG8_MMA(1, 1, At, B1); PG8_BAR; PG8_SCHED;
;             PG8_LDB(B0, 1, 0); PG8_LDB(B1, 1, 1); PG8_SCHED; PG8_LDA(At, 1, 0); PG8_STAGE(PG8_SA(0, 1), a2 + hstep, voffA);
;             PG8_WAIT_V(8); PG8_WAIT_L(0); PG8_BAR; PG8_MMA(0, 0, At, B0); PG8_MMA(0, 1, At, B1); PG8_BAR; PG8_SCHED;
	s_setprio 1
	v_mfma_f32_16x16x32_bf16 v[64:67], v[144:147], v[180:183], v[64:67]
	v_mfma_f32_16x16x32_bf16 v[56:59], v[152:155], v[180:183], v[56:59]
	v_mfma_f32_16x16x32_bf16 v[48:51], v[144:147], v[188:191], v[48:51]
	v_mfma_f32_16x16x32_bf16 v[40:43], v[152:155], v[188:191], v[40:43]
	v_mfma_f32_16x16x32_bf16 v[32:35], v[144:147], v[202:205], v[32:35]
	v_mfma_f32_16x16x32_bf16 v[24:27], v[152:155], v[202:205], v[24:27]
	v_mfma_f32_16x16x32_bf16 v[16:19], v[144:147], v[210:213], v[16:19]
	v_mfma_f32_16x16x32_bf16 v[8:11], v[152:155], v[210:213], v[8:11]
	v_mfma_f32_16x16x32_bf16 v[64:67], v[148:151], v[184:187], v[64:67]
	v_mfma_f32_16x16x32_bf16 v[56:59], v[156:159], v[184:187], v[56:59]
	v_mfma_f32_16x16x32_bf16 v[48:51], v[148:151], v[192:195], v[48:51]
	v_mfma_f32_16x16x32_bf16 v[40:43], v[156:159], v[192:195], v[40:43]
	v_mfma_f32_16x16x32_bf16 v[32:35], v[148:151], v[206:209], v[32:35]
	v_mfma_f32_16x16x32_bf16 v[24:27], v[156:159], v[206:209], v[24:27]
	v_mfma_f32_16x16x32_bf16 v[16:19], v[148:151], v[214:217], v[16:19]
	v_mfma_f32_16x16x32_bf16 v[8:11], v[156:159], v[214:217], v[8:11]
	s_setprio 0
	s_setprio 1
	v_mfma_f32_16x16x32_bf16 v[60:63], v[160:163], v[180:183], v[60:63]
	v_mfma_f32_16x16x32_bf16 v[52:55], v[172:175], v[180:183], v[52:55]
	v_mfma_f32_16x16x32_bf16 v[44:47], v[160:163], v[188:191], v[44:47]
	v_mfma_f32_16x16x32_bf16 v[36:39], v[172:175], v[188:191], v[36:39]
	v_mfma_f32_16x16x32_bf16 v[28:31], v[160:163], v[202:205], v[28:31]
	v_mfma_f32_16x16x32_bf16 v[20:23], v[172:175], v[202:205], v[20:23]
	v_mfma_f32_16x16x32_bf16 v[12:15], v[160:163], v[210:213], v[12:15]
	v_mfma_f32_16x16x32_bf16 v[4:7], v[172:175], v[210:213], v[4:7]
	v_mfma_f32_16x16x32_bf16 v[60:63], v[168:171], v[184:187], v[60:63]
	v_mfma_f32_16x16x32_bf16 v[52:55], v[176:179], v[184:187], v[52:55]
	v_mfma_f32_16x16x32_bf16 v[44:47], v[168:171], v[192:195], v[44:47]
	v_mfma_f32_16x16x32_bf16 v[36:39], v[176:179], v[192:195], v[36:39]
	v_mfma_f32_16x16x32_bf16 v[28:31], v[168:171], v[206:209], v[28:31]
	v_mfma_f32_16x16x32_bf16 v[20:23], v[176:179], v[206:209], v[20:23]
	v_mfma_f32_16x16x32_bf16 v[12:15], v[168:171], v[214:217], v[12:15]
	v_mfma_f32_16x16x32_bf16 v[4:7], v[176:179], v[214:217], v[4:7]
	s_setprio 0
	s_barrier
	s_add_i32 s48, 0, 0x1c000
	v_add_u32_e32 v156, s47, v164
	v_add_u32_e32 v167, s48, v164
	ds_read_b128 v[144:147], v156
	ds_read_b128 v[148:151], v156 offset:1024
	ds_read_b128 v[152:155], v156 offset:2048
	ds_read_b128 v[156:159], v156 offset:3072
	ds_read_b128 v[160:163], v167
	ds_read_b128 v[168:171], v167 offset:1024
	ds_read_b128 v[172:175], v167 offset:2048
	ds_read_b128 v[176:179], v167 offset:3072
	s_add_u32 s26, s26, 0x40000
	s_addc_u32 s27, s27, 0
	s_mov_b32 m0, s39
	v_lshl_add_u64 v[224:225], s[26:27], 0, v[136:137]
	ds_read_b128 v[180:183], v166 offset:32768
	ds_read_b128 v[184:187], v166 offset:33792
	ds_read_b128 v[188:191], v166 offset:34816
	ds_read_b128 v[192:195], v166 offset:35840
	ds_read_b128 v[202:205], v166 offset:36864
	ds_read_b128 v[206:209], v166 offset:37888
	ds_read_b128 v[210:213], v166 offset:38912
	ds_read_b128 v[214:217], v166 offset:39936
	global_load_lds_dwordx4 v[224:225], off
	s_mov_b32 m0, s40
	v_lshl_add_u64 v[224:225], s[26:27], 0, v[132:133]
	global_load_lds_dwordx4 v[224:225], off
	s_waitcnt vmcnt(8) lgkmcnt(0)
	s_barrier
	s_setprio 1
	v_mfma_f32_16x16x32_bf16 v[128:131], v[144:147], v[180:183], v[128:131]
	v_mfma_f32_16x16x32_bf16 v[120:123], v[152:155], v[180:183], v[120:123]
	v_mfma_f32_16x16x32_bf16 v[112:115], v[144:147], v[188:191], v[112:115]
	v_mfma_f32_16x16x32_bf16 v[104:107], v[152:155], v[188:191], v[104:107]
	v_mfma_f32_16x16x32_bf16 v[96:99], v[144:147], v[202:205], v[96:99]
	v_mfma_f32_16x16x32_bf16 v[88:91], v[152:155], v[202:205], v[88:91]
	v_mfma_f32_16x16x32_bf16 v[80:83], v[144:147], v[210:213], v[80:83]
	v_mfma_f32_16x16x32_bf16 v[72:75], v[152:155], v[210:213], v[72:75]
	v_mfma_f32_16x16x32_bf16 v[128:131], v[148:151], v[184:187], v[128:131]
	v_mfma_f32_16x16x32_bf16 v[120:123], v[156:159], v[184:187], v[120:123]
	v_mfma_f32_16x16x32_bf16 v[112:115], v[148:151], v[192:195], v[112:115]
	v_mfma_f32_16x16x32_bf16 v[104:107], v[156:159], v[192:195], v[104:107]
	v_mfma_f32_16x16x32_bf16 v[96:99], v[148:151], v[206:209], v[96:99]
	v_mfma_f32_16x16x32_bf16 v[88:91], v[156:159], v[206:209], v[88:91]
	v_mfma_f32_16x16x32_bf16 v[80:83], v[148:151], v[214:217], v[80:83]
	v_mfma_f32_16x16x32_bf16 v[72:75], v[156:159], v[214:217], v[72:75]
	s_setprio 0
	s_setprio 1
	v_mfma_f32_16x16x32_bf16 v[124:127], v[160:163], v[180:183], v[124:127]
	v_mfma_f32_16x16x32_bf16 v[116:119], v[172:175], v[180:183], v[116:119]
	v_mfma_f32_16x16x32_bf16 v[108:111], v[160:163], v[188:191], v[108:111]
	v_mfma_f32_16x16x32_bf16 v[100:103], v[172:175], v[188:191], v[100:103]
	v_mfma_f32_16x16x32_bf16 v[92:95], v[160:163], v[202:205], v[92:95]
	v_mfma_f32_16x16x32_bf16 v[84:87], v[172:175], v[202:205], v[84:87]
	v_mfma_f32_16x16x32_bf16 v[76:79], v[160:163], v[210:213], v[76:79]
	v_mfma_f32_16x16x32_bf16 v[68:71], v[172:175], v[210:213], v[68:71]
	v_mfma_f32_16x16x32_bf16 v[124:127], v[168:171], v[184:187], v[124:127]
	v_mfma_f32_16x16x32_bf16 v[116:119], v[176:179], v[184:187], v[116:119]
	v_mfma_f32_16x16x32_bf16 v[108:111], v[168:171], v[192:195], v[108:111]
	v_mfma_f32_16x16x32_bf16 v[100:103], v[176:179], v[192:195], v[100:103]
	v_mfma_f32_16x16x32_bf16 v[92:95], v[168:171], v[206:209], v[92:95]
	v_mfma_f32_16x16x32_bf16 v[84:87], v[176:179], v[206:209], v[84:87]
	v_mfma_f32_16x16x32_bf16 v[76:79], v[168:171], v[214:217], v[76:79]
	v_mfma_f32_16x16x32_bf16 v[68:71], v[176:179], v[214:217], v[68:71]
	s_setprio 0
	s_barrier
; #define PG8_STAGE(bufoff, gbase, voff) do { _Pragma("unroll") for (int _i = 0; _i < 2; ++_i) \
;         __builtin_amdgcn_global_load_lds((const unsigned*)((const char*)(gbase) + (voff)[_i]), (PG8_LAS unsigned*)(lds + (bufoff) + ldsw + _i * 8192), 16, 0, 0); } while (0)
; #define PG8_LDA(dst, b, h) do { _Pragma("unroll") for (int m = 0; m < 4; ++m) _Pragma("unroll") for (int k = 0; k < 2; ++k) dst[m][k] = *(const PG8_LAS bf16x8*)(lds + PG8_SA(b, h) + aoff + m * 2048 + k * 1024); } while (0)
; #define PG8_MMA(ai, bj, At, Bt) do { __builtin_amdgcn_s_setprio(1); _Pragma("unroll") for (int m = 0; m < 4; ++m) _Pragma("unroll") for (int n = 0; n < 2; ++n) _Pragma("unroll") for (int k = 0; k < 2; ++k) \
;         acc[ai][bj][m][n] = __builtin_amdgcn_mfma_f32_16x16x32_bf16(Bt[n][k], At[m][k], acc[ai][bj][m][n], 0, 0, 0); __builtin_amdgcn_s_setprio(0); } while (0)
; #define PG8_WAIT_V(n) asm volatile("s_waitcnt vmcnt(" #n ")" ::: "memory")
; #define PG8_WAIT_L(n) asm volatile("s_waitcnt lgkmcnt(" #n ")" ::: "memory")
; #define PG8_BAR __builtin_amdgcn_s_barrier()
; #define PG8_SCHED __builtin_amdgcn_sched_barrier(0)
; template <class Epi, class Sched, bool ALIGN_EPI = false, bool SP2 = false>
; __device__ __forceinline__ void gemm_phase(PG8_LAS unsigned char* lds, const Gemm g, const Sched& S, const Epi& E) {
;     ...
;         for (int t = 0; t < nt; t += 2) {
;             const bool last = (t == nt - 2);
;             const char* a1 = cA + (size_t)(t + 1) * kstep;
;             const char* a2 = last ? nA : cA + (size_t)(t + 2) * kstep; const char* b2 = last ? nB : cB + (size_t)(t + 2) * kstep;
;     ...
;             PG8_LDA(At, 1, 1); PG8_STAGE(PG8_SB(1, 0), b3, voffB); PG8_STAGE(PG8_SB(1, 1), b3 + hstep, voffB); PG8_STAGE(PG8_SA(1, 0), a3, voffA);
;             PG8_WAIT_V(8); PG8_WAIT_L(0); PG8_BAR; PG8_MMA(1, 0, At, B0); PG8_MMA(1, 1, At, B1); PG8_BAR; PG8_SCHED;
	s_add_i32 s26, s47, s35
	v_lshl_add_u64 v[198:199], v[198:199], 0, s[82:83]
	s_mov_b32 m0, s26
	ds_read_b128 v[180:183], v166 offset:49152
	ds_read_b128 v[184:187], v166 offset:50176
	ds_read_b128 v[188:191], v166 offset:51200
	ds_read_b128 v[192:195], v166 offset:52224
	ds_read_b128 v[202:205], v166 offset:53248
	ds_read_b128 v[206:209], v166 offset:54272
	ds_read_b128 v[210:213], v166 offset:55296
	ds_read_b128 v[214:217], v166 offset:56320
	global_load_lds_dwordx4 v[198:199], off
	s_add_i32 m0, s26, 0x2000
	s_add_u32 s24, s24, 0x40080
	v_lshl_add_u64 v[198:199], v[218:219], 0, s[82:83]
	s_addc_u32 s25, s25, 0
	s_add_i32 s26, s48, s35
	global_load_lds_dwordx4 v[198:199], off
	s_mov_b32 m0, s26
	v_lshl_add_u64 v[198:199], s[24:25], 0, v[134:135]
	global_load_lds_dwordx4 v[198:199], off
	s_add_i32 m0, s26, 0x2000
	v_lshl_add_u64 v[198:199], s[24:25], 0, v[0:1]
	global_load_lds_dwordx4 v[198:199], off
	s_mov_b32 m0, s41
	v_lshl_add_u64 v[198:199], v[220:221], 0, s[82:83]
	global_load_lds_dwordx4 v[198:199], off
	s_mov_b32 m0, s42
	v_lshl_add_u64 v[198:199], v[222:223], 0, s[82:83]
	global_load_lds_dwordx4 v[198:199], off
	s_waitcnt vmcnt(8) lgkmcnt(0)
	s_barrier
	s_setprio 1
	v_mfma_f32_16x16x32_bf16 v[64:67], v[144:147], v[180:183], v[64:67]
	v_mfma_f32_16x16x32_bf16 v[56:59], v[152:155], v[180:183], v[56:59]
	v_mfma_f32_16x16x32_bf16 v[48:51], v[144:147], v[188:191], v[48:51]
	v_mfma_f32_16x16x32_bf16 v[40:43], v[152:155], v[188:191], v[40:43]
	v_mfma_f32_16x16x32_bf16 v[32:35], v[144:147], v[202:205], v[32:35]
	v_mfma_f32_16x16x32_bf16 v[24:27], v[152:155], v[202:205], v[24:27]
	v_mfma_f32_16x16x32_bf16 v[16:19], v[144:147], v[210:213], v[16:19]
	v_mfma_f32_16x16x32_bf16 v[8:11], v[152:155], v[210:213], v[8:11]
	v_mfma_f32_16x16x32_bf16 v[64:67], v[148:151], v[184:187], v[64:67]
	v_mfma_f32_16x16x32_bf16 v[56:59], v[156:159], v[184:187], v[56:59]
	v_mfma_f32_16x16x32_bf16 v[48:51], v[148:151], v[192:195], v[48:51]
	v_mfma_f32_16x16x32_bf16 v[40:43], v[156:159], v[192:195], v[40:43]
	v_mfma_f32_16x16x32_bf16 v[32:35], v[148:151], v[206:209], v[32:35]
	v_mfma_f32_16x16x32_bf16 v[24:27], v[156:159], v[206:209], v[24:27]
	v_mfma_f32_16x16x32_bf16 v[16:19], v[148:151], v[214:217], v[16:19]
	v_mfma_f32_16x16x32_bf16 v[8:11], v[156:159], v[214:217], v[8:11]
	s_setprio 0
	s_setprio 1
	v_mfma_f32_16x16x32_bf16 v[60:63], v[160:163], v[180:183], v[60:63]
	v_mfma_f32_16x16x32_bf16 v[52:55], v[172:175], v[180:183], v[52:55]
	v_mfma_f32_16x16x32_bf16 v[44:47], v[160:163], v[188:191], v[44:47]
	v_mfma_f32_16x16x32_bf16 v[36:39], v[172:175], v[188:191], v[36:39]
	v_mfma_f32_16x16x32_bf16 v[28:31], v[160:163], v[202:205], v[28:31]
	v_mfma_f32_16x16x32_bf16 v[20:23], v[172:175], v[202:205], v[20:23]
	v_mfma_f32_16x16x32_bf16 v[12:15], v[160:163], v[210:213], v[12:15]
	v_mfma_f32_16x16x32_bf16 v[4:7], v[172:175], v[210:213], v[4:7]
	v_mfma_f32_16x16x32_bf16 v[60:63], v[168:171], v[184:187], v[60:63]
	v_mfma_f32_16x16x32_bf16 v[52:55], v[176:179], v[184:187], v[52:55]
	v_mfma_f32_16x16x32_bf16 v[44:47], v[168:171], v[192:195], v[44:47]
	v_mfma_f32_16x16x32_bf16 v[36:39], v[176:179], v[192:195], v[36:39]
	v_mfma_f32_16x16x32_bf16 v[28:31], v[168:171], v[206:209], v[28:31]
	v_mfma_f32_16x16x32_bf16 v[20:23], v[176:179], v[206:209], v[20:23]
	v_mfma_f32_16x16x32_bf16 v[12:15], v[168:171], v[214:217], v[12:15]
	v_mfma_f32_16x16x32_bf16 v[4:7], v[176:179], v[214:217], v[4:7]
	s_setprio 0
	s_barrier
	s_add_i32 s46, s46, 2
	s_add_u32 s8, s8, 0x100
	s_addc_u32 s9, s9, 0
	s_add_u32 s44, s44, 0x100
	s_addc_u32 s45, s45, 0
	s_cmp_gt_u32 s46, 13
	s_cbranch_scc0 .LBB0_405
	s_and_b64 vcc, exec, s[14:15]
	s_cbranch_vccz .LBB0_408
	s_barrier

; #define PG8_STAGE(bufoff, gbase, voff) do { _Pragma("unroll") for (int _i = 0; _i < 2; ++_i) \
;         __builtin_amdgcn_global_load_lds((const unsigned*)((const char*)(gbase) + (voff)[_i]), (PG8_LAS unsigned*)(lds + (bufoff) + ldsw + _i * 8192), 16, 0, 0); } while (0)
; #define PG8_LDA(dst, b, h) do { _Pragma("unroll") for (int m = 0; m < 4; ++m) _Pragma("unroll") for (int k = 0; k < 2; ++k) dst[m][k] = *(const PG8_LAS bf16x8*)(lds + PG8_SA(b, h) + aoff + m * 2048 + k * 1024); } while (0)
; #define PG8_LDB(dst, b, h) do { _Pragma("unroll") for (int n = 0; n < 2; ++n) _Pragma("unroll") for (int k = 0; k < 2; ++k) dst[n][k] = *(const PG8_LAS bf16x8*)(lds + PG8_SB(b, h) + boff + n * 2048 + k * 1024); } while (0)
; #define PG8_MMA(ai, bj, At, Bt) do { __builtin_amdgcn_s_setprio(1); _Pragma("unroll") for (int m = 0; m < 4; ++m) _Pragma("unroll") for (int n = 0; n < 2; ++n) _Pragma("unroll") for (int k = 0; k < 2; ++k) \
;         acc[ai][bj][m][n] = __builtin_amdgcn_mfma_f32_16x16x32_bf16(Bt[n][k], At[m][k], acc[ai][bj][m][n], 0, 0, 0); __builtin_amdgcn_s_setprio(0); } while (0)
; #define PG8_WAIT_V(n) asm volatile("s_waitcnt vmcnt(" #n ")" ::: "memory")
; #define PG8_WAIT_L(n) asm volatile("s_waitcnt lgkmcnt(" #n ")" ::: "memory")
; #define PG8_BAR __builtin_amdgcn_s_barrier()
; #define PG8_SCHED __builtin_amdgcn_sched_barrier(0)
; template <class Epi, class Sched, bool ALIGN_EPI = false, bool SP2 = false>
; __device__ __forceinline__ void gemm_phase(PG8_LAS unsigned char* lds, const Gemm g, const Sched& S, const Epi& E) {
;     ...
;         for (int t = 0; t < nt; t += 2) {
;             const bool last = (t == nt - 2);
;             const char* a1 = cA + (size_t)(t + 1) * kstep;
;             const char* a2 = last ? nA : cA + (size_t)(t + 2) * kstep; const char* b2 = last ? nB : cB + (size_t)(t + 2) * kstep;
;             const char* a3 = a2 + kstep; const char* b3 = b2 + kstep;
;             if (last && has_next) S.a_ready(nxt);
;             if constexpr (SP2) {
;             PG8_LDB(B0, 0, 0); PG8_LDB(B1, 0, 1); PG8_SCHED; PG8_LDA(At, 0, 0); PG8_STAGE(PG8_SA(1, 1), a1 + hstep, voffA);
;             PG8_WAIT_V(8); PG8_WAIT_L(0); PG8_BAR; PG8_MMA(0, 0, At, B0); PG8_MMA(0, 1, At, B1); PG8_BAR; PG8_SCHED;
;             PG8_LDA(At, 0, 1); PG8_STAGE(PG8_SB(0, 0), b2, voffB); PG8_STAGE(PG8_SB(0, 1), b2 + hstep, voffB); PG8_STAGE(PG8_SA(0, 0), a2, voffA);
.LBB0_480:
	s_add_u32 s8, s26, 0x100
	s_addc_u32 s9, s27, 0
	s_add_i32 s54, 0, 0x10000
	s_cmp_eq_u32 s53, 40
	s_cselect_b32 s31, s23, s9
	s_cselect_b32 s30, s22, s8
	s_cselect_b32 s29, s25, s45
	s_cselect_b32 s28, s24, s44
	s_add_i32 s55, 0, 0x14000
	v_add_u32_e32 v100, s54, v234
	v_add_u32_e32 v144, s55, v234
	ds_read_b128 v[68:71], v100
	ds_read_b128 v[80:83], v100 offset:1024
	ds_read_b128 v[92:95], v100 offset:2048
	ds_read_b128 v[100:103], v100 offset:3072
	ds_read_b128 v[112:115], v144
	ds_read_b128 v[120:123], v144 offset:1024
	ds_read_b128 v[132:135], v144 offset:2048
	ds_read_b128 v[144:147], v144 offset:3072
	v_lshl_add_u64 v[198:199], s[26:27], 0, v[204:205]
	s_add_i32 m0, s40, 0xc000
	ds_read_b128 v[156:159], v236
	ds_read_b128 v[168:171], v236 offset:1024
	ds_read_b128 v[172:175], v236 offset:2048
	ds_read_b128 v[176:179], v236 offset:3072
	ds_read_b128 v[180:183], v236 offset:4096
	ds_read_b128 v[184:187], v236 offset:5120
	ds_read_b128 v[188:191], v236 offset:6144
	ds_read_b128 v[208:211], v236 offset:7168
	global_load_lds_dwordx4 v[198:199], off
	s_add_i32 m0, s40, 0xe000
	v_lshl_add_u64 v[198:199], s[26:27], 0, v[206:207]
	global_load_lds_dwordx4 v[198:199], off
	s_waitcnt vmcnt(8) lgkmcnt(0)
	s_barrier
	s_setprio 1
	v_mfma_f32_16x16x32_bf16 v[164:167], v[68:71], v[156:159], v[164:167]
	v_mfma_f32_16x16x32_bf16 v[160:163], v[92:95], v[156:159], v[160:163]
	v_mfma_f32_16x16x32_bf16 v[140:143], v[68:71], v[172:175], v[140:143]
	v_mfma_f32_16x16x32_bf16 v[136:139], v[92:95], v[172:175], v[136:139]
	v_mfma_f32_16x16x32_bf16 v[116:119], v[68:71], v[180:183], v[116:119]
	v_mfma_f32_16x16x32_bf16 v[108:111], v[92:95], v[180:183], v[108:111]
	v_mfma_f32_16x16x32_bf16 v[88:91], v[68:71], v[188:191], v[88:91]
	v_mfma_f32_16x16x32_bf16 v[84:87], v[92:95], v[188:191], v[84:87]
	v_mfma_f32_16x16x32_bf16 v[164:167], v[80:83], v[168:171], v[164:167]
	v_mfma_f32_16x16x32_bf16 v[160:163], v[100:103], v[168:171], v[160:163]
	v_mfma_f32_16x16x32_bf16 v[140:143], v[80:83], v[176:179], v[140:143]
	v_mfma_f32_16x16x32_bf16 v[136:139], v[100:103], v[176:179], v[136:139]
	v_mfma_f32_16x16x32_bf16 v[116:119], v[80:83], v[184:187], v[116:119]
	v_mfma_f32_16x16x32_bf16 v[108:111], v[100:103], v[184:187], v[108:111]
	v_mfma_f32_16x16x32_bf16 v[88:91], v[80:83], v[208:211], v[88:91]
	v_mfma_f32_16x16x32_bf16 v[84:87], v[100:103], v[208:211], v[84:87]
	s_setprio 0
	s_setprio 1
	v_mfma_f32_16x16x32_bf16 v[152:155], v[112:115], v[156:159], v[152:155]
	v_mfma_f32_16x16x32_bf16 v[148:151], v[132:135], v[156:159], v[148:151]
	v_mfma_f32_16x16x32_bf16 v[128:131], v[112:115], v[172:175], v[128:131]
	v_mfma_f32_16x16x32_bf16 v[124:127], v[132:135], v[172:175], v[124:127]
	v_mfma_f32_16x16x32_bf16 v[104:107], v[112:115], v[180:183], v[104:107]
	v_mfma_f32_16x16x32_bf16 v[96:99], v[132:135], v[180:183], v[96:99]
	v_mfma_f32_16x16x32_bf16 v[76:79], v[112:115], v[188:191], v[76:79]
	v_mfma_f32_16x16x32_bf16 v[72:75], v[132:135], v[188:191], v[72:75]
	v_mfma_f32_16x16x32_bf16 v[152:155], v[120:123], v[168:171], v[152:155]
	v_mfma_f32_16x16x32_bf16 v[148:151], v[144:147], v[168:171], v[148:151]
	v_mfma_f32_16x16x32_bf16 v[128:131], v[120:123], v[176:179], v[128:131]
	v_mfma_f32_16x16x32_bf16 v[124:127], v[144:147], v[176:179], v[124:127]
	v_mfma_f32_16x16x32_bf16 v[104:107], v[120:123], v[184:187], v[104:107]
	v_mfma_f32_16x16x32_bf16 v[96:99], v[144:147], v[184:187], v[96:99]
	v_mfma_f32_16x16x32_bf16 v[76:79], v[120:123], v[208:211], v[76:79]
	v_mfma_f32_16x16x32_bf16 v[72:75], v[144:147], v[208:211], v[72:75]
	s_setprio 0
	s_barrier
	s_add_i32 s26, s54, s39
	v_lshl_add_u64 v[198:199], s[28:29], 0, v[192:193]
	s_mov_b32 m0, s26
	ds_read_b128 v[156:159], v236 offset:16384
	ds_read_b128 v[168:171], v236 offset:17408
	ds_read_b128 v[172:175], v236 offset:18432
	ds_read_b128 v[176:179], v236 offset:19456
	ds_read_b128 v[180:183], v236 offset:20480
	ds_read_b128 v[184:187], v236 offset:21504
	ds_read_b128 v[188:191], v236 offset:22528
	ds_read_b128 v[208:211], v236 offset:23552
	global_load_lds_dwordx4 v[198:199], off
	s_add_i32 m0, s26, 0x2000
	s_add_u32 s26, s28, 0xb0000
	v_lshl_add_u64 v[212:213], s[28:29], 0, v[202:203]
	s_addc_u32 s27, s29, 0
	s_add_i32 s54, s55, s39
	global_load_lds_dwordx4 v[212:213], off
	v_lshl_add_u64 v[214:215], s[26:27], 0, v[192:193]
	s_mov_b32 m0, s54
	v_lshl_add_u64 v[216:217], s[30:31], 0, v[194:195]
	global_load_lds_dwordx4 v[214:215], off
	s_add_i32 m0, s54, 0x2000
	v_lshl_add_u64 v[214:215], s[26:27], 0, v[202:203]
	global_load_lds_dwordx4 v[214:215], off
	s_mov_b32 m0, s40
	v_lshl_add_u64 v[214:215], s[30:31], 0, v[0:1]
	global_load_lds_dwordx4 v[214:215], off
	s_mov_b32 m0, s41
	s_add_i32 s54, 0, 0x18000
	global_load_lds_dwordx4 v[216:217], off
	s_waitcnt vmcnt(8) lgkmcnt(0)
	s_barrier
; #define PG8_STAGE(bufoff, gbase, voff) do { _Pragma("unroll") for (int _i = 0; _i < 2; ++_i) \
;         __builtin_amdgcn_global_load_lds((const unsigned*)((const char*)(gbase) + (voff)[_i]), (PG8_LAS unsigned*)(lds + (bufoff) + ldsw + _i * 8192), 16, 0, 0); } while (0)
; #define PG8_LDA(dst, b, h) do { _Pragma("unroll") for (int m = 0; m < 4; ++m) _Pragma("unroll") for (int k = 0; k < 2; ++k) dst[m][k] = *(const PG8_LAS bf16x8*)(lds + PG8_SA(b, h) + aoff + m * 2048 + k * 1024); } while (0)
; #define PG8_LDB(dst, b, h) do { _Pragma("unroll") for (int n = 0; n < 2; ++n) _Pragma("unroll") for (int k = 0; k < 2; ++k) dst[n][k] = *(const PG8_LAS bf16x8*)(lds + PG8_SB(b, h) + boff + n * 2048 + k * 1024); } while (0)
; #define PG8_MMA(ai, bj, At, Bt) do { __builtin_amdgcn_s_setprio(1); _Pragma("unroll") for (int m = 0; m < 4; ++m) _Pragma("unroll") for (int n = 0; n < 2; ++n) _Pragma("unroll") for (int k = 0; k < 2; ++k) \
;         acc[ai][bj][m][n] = __builtin_amdgcn_mfma_f32_16x16x32_bf16(Bt[n][k], At[m][k], acc[ai][bj][m][n], 0, 0, 0); __builtin_amdgcn_s_setprio(0); } while (0)
; #define PG8_WAIT_V(n) asm volatile("s_waitcnt vmcnt(" #n ")" ::: "memory")
; #define PG8_WAIT_L(n) asm volatile("s_waitcnt lgkmcnt(" #n ")" ::: "memory")
; #define PG8_BAR __builtin_amdgcn_s_barrier()
; #define PG8_SCHED __builtin_amdgcn_sched_barrier(0)
; template <class Epi, class Sched, bool ALIGN_EPI = false, bool SP2 = false>
; __device__ __forceinline__ void gemm_phase(PG8_LAS unsigned char* lds, const Gemm g, const Sched& S, const Epi& E) {
;     ...
;             PG8_WAIT_V(8); PG8_WAIT_L(0); PG8_BAR; PG8_MMA(1, 0, At, B0); PG8_MMA(1, 1, At, B1); PG8_BAR; PG8_SCHED;
;             PG8_LDB(B0, 1, 0); PG8_LDB(B1, 1, 1); PG8_SCHED; PG8_LDA(At, 1, 0); PG8_STAGE(PG8_SA(0, 1), a2 + hstep, voffA);
;             PG8_WAIT_V(8); PG8_WAIT_L(0); PG8_BAR; PG8_MMA(0, 0, At, B0); PG8_MMA(0, 1, At, B1); PG8_BAR; PG8_SCHED;
	s_setprio 1
	v_mfma_f32_16x16x32_bf16 v[64:67], v[68:71], v[156:159], v[64:67]
	v_mfma_f32_16x16x32_bf16 v[60:63], v[92:95], v[156:159], v[60:63]
	v_mfma_f32_16x16x32_bf16 v[48:51], v[68:71], v[172:175], v[48:51]
	v_mfma_f32_16x16x32_bf16 v[44:47], v[92:95], v[172:175], v[44:47]
	v_mfma_f32_16x16x32_bf16 v[32:35], v[68:71], v[180:183], v[32:35]
	v_mfma_f32_16x16x32_bf16 v[28:31], v[92:95], v[180:183], v[28:31]
	v_mfma_f32_16x16x32_bf16 v[16:19], v[68:71], v[188:191], v[16:19]
	v_mfma_f32_16x16x32_bf16 v[12:15], v[92:95], v[188:191], v[12:15]
	v_mfma_f32_16x16x32_bf16 v[64:67], v[80:83], v[168:171], v[64:67]
	v_mfma_f32_16x16x32_bf16 v[60:63], v[100:103], v[168:171], v[60:63]
	v_mfma_f32_16x16x32_bf16 v[48:51], v[80:83], v[176:179], v[48:51]
	v_mfma_f32_16x16x32_bf16 v[44:47], v[100:103], v[176:179], v[44:47]
	v_mfma_f32_16x16x32_bf16 v[32:35], v[80:83], v[184:187], v[32:35]
	v_mfma_f32_16x16x32_bf16 v[28:31], v[100:103], v[184:187], v[28:31]
	v_mfma_f32_16x16x32_bf16 v[16:19], v[80:83], v[208:211], v[16:19]
	v_mfma_f32_16x16x32_bf16 v[12:15], v[100:103], v[208:211], v[12:15]
	s_setprio 0
	s_setprio 1
	v_mfma_f32_16x16x32_bf16 v[56:59], v[112:115], v[156:159], v[56:59]
	v_mfma_f32_16x16x32_bf16 v[52:55], v[132:135], v[156:159], v[52:55]
	v_mfma_f32_16x16x32_bf16 v[40:43], v[112:115], v[172:175], v[40:43]
	v_mfma_f32_16x16x32_bf16 v[36:39], v[132:135], v[172:175], v[36:39]
	v_mfma_f32_16x16x32_bf16 v[24:27], v[112:115], v[180:183], v[24:27]
	v_mfma_f32_16x16x32_bf16 v[20:23], v[132:135], v[180:183], v[20:23]
	v_mfma_f32_16x16x32_bf16 v[8:11], v[112:115], v[188:191], v[8:11]
	v_mfma_f32_16x16x32_bf16 v[4:7], v[132:135], v[188:191], v[4:7]
	v_mfma_f32_16x16x32_bf16 v[56:59], v[120:123], v[168:171], v[56:59]
	v_mfma_f32_16x16x32_bf16 v[52:55], v[144:147], v[168:171], v[52:55]
	v_mfma_f32_16x16x32_bf16 v[40:43], v[120:123], v[176:179], v[40:43]
	v_mfma_f32_16x16x32_bf16 v[36:39], v[144:147], v[176:179], v[36:39]
	v_mfma_f32_16x16x32_bf16 v[24:27], v[120:123], v[184:187], v[24:27]
	v_mfma_f32_16x16x32_bf16 v[20:23], v[144:147], v[184:187], v[20:23]
	v_mfma_f32_16x16x32_bf16 v[8:11], v[120:123], v[208:211], v[8:11]
	v_mfma_f32_16x16x32_bf16 v[4:7], v[144:147], v[208:211], v[4:7]
	s_setprio 0
	s_barrier
	s_add_i32 s55, 0, 0x1c000
	v_add_u32_e32 v100, s54, v234
	v_add_u32_e32 v144, s55, v234
	ds_read_b128 v[68:71], v100
	ds_read_b128 v[80:83], v100 offset:1024
	ds_read_b128 v[92:95], v100 offset:2048
	ds_read_b128 v[100:103], v100 offset:3072
	ds_read_b128 v[112:115], v144
	ds_read_b128 v[120:123], v144 offset:1024
	ds_read_b128 v[132:135], v144 offset:2048
	ds_read_b128 v[144:147], v144 offset:3072
	s_add_u32 s26, s30, 0xb0000
	s_addc_u32 s27, s31, 0
	s_mov_b32 m0, s42
	v_lshl_add_u64 v[218:219], s[26:27], 0, v[0:1]
	ds_read_b128 v[156:159], v236 offset:32768
	ds_read_b128 v[168:171], v236 offset:33792
	ds_read_b128 v[172:175], v236 offset:34816
	ds_read_b128 v[176:179], v236 offset:35840
	ds_read_b128 v[180:183], v236 offset:36864
	ds_read_b128 v[184:187], v236 offset:37888
	ds_read_b128 v[188:191], v236 offset:38912
	ds_read_b128 v[208:211], v236 offset:39936
	global_load_lds_dwordx4 v[218:219], off
	s_mov_b32 m0, s43
	v_lshl_add_u64 v[218:219], s[26:27], 0, v[194:195]
	global_load_lds_dwordx4 v[218:219], off
	s_waitcnt vmcnt(8) lgkmcnt(0)
	s_barrier
	s_setprio 1
	v_mfma_f32_16x16x32_bf16 v[164:167], v[68:71], v[156:159], v[164:167]
	v_mfma_f32_16x16x32_bf16 v[160:163], v[92:95], v[156:159], v[160:163]
	v_mfma_f32_16x16x32_bf16 v[140:143], v[68:71], v[172:175], v[140:143]
	v_mfma_f32_16x16x32_bf16 v[136:139], v[92:95], v[172:175], v[136:139]
	v_mfma_f32_16x16x32_bf16 v[116:119], v[68:71], v[180:183], v[116:119]
	v_mfma_f32_16x16x32_bf16 v[108:111], v[92:95], v[180:183], v[108:111]
	v_mfma_f32_16x16x32_bf16 v[88:91], v[68:71], v[188:191], v[88:91]
	v_mfma_f32_16x16x32_bf16 v[84:87], v[92:95], v[188:191], v[84:87]
	v_mfma_f32_16x16x32_bf16 v[164:167], v[80:83], v[168:171], v[164:167]
	v_mfma_f32_16x16x32_bf16 v[160:163], v[100:103], v[168:171], v[160:163]
	v_mfma_f32_16x16x32_bf16 v[140:143], v[80:83], v[176:179], v[140:143]
	v_mfma_f32_16x16x32_bf16 v[136:139], v[100:103], v[176:179], v[136:139]
	v_mfma_f32_16x16x32_bf16 v[116:119], v[80:83], v[184:187], v[116:119]
	v_mfma_f32_16x16x32_bf16 v[108:111], v[100:103], v[184:187], v[108:111]
	v_mfma_f32_16x16x32_bf16 v[88:91], v[80:83], v[208:211], v[88:91]
	v_mfma_f32_16x16x32_bf16 v[84:87], v[100:103], v[208:211], v[84:87]
	s_setprio 0
	s_setprio 1
	v_mfma_f32_16x16x32_bf16 v[152:155], v[112:115], v[156:159], v[152:155]
	v_mfma_f32_16x16x32_bf16 v[148:151], v[132:135], v[156:159], v[148:151]
	v_mfma_f32_16x16x32_bf16 v[128:131], v[112:115], v[172:175], v[128:131]
	v_mfma_f32_16x16x32_bf16 v[124:127], v[132:135], v[172:175], v[124:127]
	v_mfma_f32_16x16x32_bf16 v[104:107], v[112:115], v[180:183], v[104:107]
	v_mfma_f32_16x16x32_bf16 v[96:99], v[132:135], v[180:183], v[96:99]
	v_mfma_f32_16x16x32_bf16 v[76:79], v[112:115], v[188:191], v[76:79]
	v_mfma_f32_16x16x32_bf16 v[72:75], v[132:135], v[188:191], v[72:75]
	v_mfma_f32_16x16x32_bf16 v[152:155], v[120:123], v[168:171], v[152:155]
	v_mfma_f32_16x16x32_bf16 v[148:151], v[144:147], v[168:171], v[148:151]
	v_mfma_f32_16x16x32_bf16 v[128:131], v[120:123], v[176:179], v[128:131]
	v_mfma_f32_16x16x32_bf16 v[124:127], v[144:147], v[176:179], v[124:127]
	v_mfma_f32_16x16x32_bf16 v[104:107], v[120:123], v[184:187], v[104:107]
	v_mfma_f32_16x16x32_bf16 v[96:99], v[144:147], v[184:187], v[96:99]
	v_mfma_f32_16x16x32_bf16 v[76:79], v[120:123], v[208:211], v[76:79]
	v_mfma_f32_16x16x32_bf16 v[72:75], v[144:147], v[208:211], v[72:75]
	s_setprio 0
	s_barrier
; #define PG8_STAGE(bufoff, gbase, voff) do { _Pragma("unroll") for (int _i = 0; _i < 2; ++_i) \
;         __builtin_amdgcn_global_load_lds((const unsigned*)((const char*)(gbase) + (voff)[_i]), (PG8_LAS unsigned*)(lds + (bufoff) + ldsw + _i * 8192), 16, 0, 0); } while (0)
; #define PG8_LDA(dst, b, h) do { _Pragma("unroll") for (int m = 0; m < 4; ++m) _Pragma("unroll") for (int k = 0; k < 2; ++k) dst[m][k] = *(const PG8_LAS bf16x8*)(lds + PG8_SA(b, h) + aoff + m * 2048 + k * 1024); } while (0)
; #define PG8_MMA(ai, bj, At, Bt) do { __builtin_amdgcn_s_setprio(1); _Pragma("unroll") for (int m = 0; m < 4; ++m) _Pragma("unroll") for (int n = 0; n < 2; ++n) _Pragma("unroll") for (int k = 0; k < 2; ++k) \
;         acc[ai][bj][m][n] = __builtin_amdgcn_mfma_f32_16x16x32_bf16(Bt[n][k], At[m][k], acc[ai][bj][m][n], 0, 0, 0); __builtin_amdgcn_s_setprio(0); } while (0)
; #define PG8_WAIT_V(n) asm volatile("s_waitcnt vmcnt(" #n ")" ::: "memory")
; #define PG8_WAIT_L(n) asm volatile("s_waitcnt lgkmcnt(" #n ")" ::: "memory")
; #define PG8_BAR __builtin_amdgcn_s_barrier()
; #define PG8_SCHED __builtin_amdgcn_sched_barrier(0)
; template <class Epi, class Sched, bool ALIGN_EPI = false, bool SP2 = false>
; __device__ __forceinline__ void gemm_phase(PG8_LAS unsigned char* lds, const Gemm g, const Sched& S, const Epi& E) {
;     ...
;         for (int t = 0; t < nt; t += 2) {
;             const bool last = (t == nt - 2);
;             const char* a1 = cA + (size_t)(t + 1) * kstep;
;             const char* a2 = last ? nA : cA + (size_t)(t + 2) * kstep; const char* b2 = last ? nB : cB + (size_t)(t + 2) * kstep;
;     ...
;             PG8_LDA(At, 1, 1); PG8_STAGE(PG8_SB(1, 0), b3, voffB); PG8_STAGE(PG8_SB(1, 1), b3 + hstep, voffB); PG8_STAGE(PG8_SA(1, 0), a3, voffA);
;             PG8_WAIT_V(8); PG8_WAIT_L(0); PG8_BAR; PG8_MMA(1, 0, At, B0); PG8_MMA(1, 1, At, B1); PG8_BAR; PG8_SCHED;
	s_add_i32 s26, s54, s39
	v_lshl_add_u64 v[198:199], v[198:199], 0, s[82:83]
	s_mov_b32 m0, s26
	ds_read_b128 v[156:159], v236 offset:49152
	ds_read_b128 v[168:171], v236 offset:50176
	ds_read_b128 v[172:175], v236 offset:51200
	ds_read_b128 v[176:179], v236 offset:52224
	ds_read_b128 v[180:183], v236 offset:53248
	ds_read_b128 v[184:187], v236 offset:54272
	ds_read_b128 v[188:191], v236 offset:55296
	ds_read_b128 v[208:211], v236 offset:56320
	global_load_lds_dwordx4 v[198:199], off
	s_add_i32 m0, s26, 0x2000
	s_add_u32 s26, s28, 0xb0080
	v_lshl_add_u64 v[198:199], v[212:213], 0, s[82:83]
	s_addc_u32 s27, s29, 0
	s_add_i32 s28, s55, s39
	global_load_lds_dwordx4 v[198:199], off
	s_mov_b32 m0, s28
	v_lshl_add_u64 v[198:199], s[26:27], 0, v[192:193]
	global_load_lds_dwordx4 v[198:199], off
	s_add_i32 m0, s28, 0x2000
	v_lshl_add_u64 v[198:199], s[26:27], 0, v[202:203]
	global_load_lds_dwordx4 v[198:199], off
	s_mov_b32 m0, s47
	v_lshl_add_u64 v[198:199], v[214:215], 0, s[82:83]
	global_load_lds_dwordx4 v[198:199], off
	s_mov_b32 m0, s48
	v_lshl_add_u64 v[198:199], v[216:217], 0, s[82:83]
	global_load_lds_dwordx4 v[198:199], off
	s_waitcnt vmcnt(8) lgkmcnt(0)
	s_barrier
	s_setprio 1
	v_mfma_f32_16x16x32_bf16 v[64:67], v[68:71], v[156:159], v[64:67]
	v_mfma_f32_16x16x32_bf16 v[60:63], v[92:95], v[156:159], v[60:63]
	v_mfma_f32_16x16x32_bf16 v[48:51], v[68:71], v[172:175], v[48:51]
	v_mfma_f32_16x16x32_bf16 v[44:47], v[92:95], v[172:175], v[44:47]
	v_mfma_f32_16x16x32_bf16 v[32:35], v[68:71], v[180:183], v[32:35]
	v_mfma_f32_16x16x32_bf16 v[28:31], v[92:95], v[180:183], v[28:31]
	v_mfma_f32_16x16x32_bf16 v[16:19], v[68:71], v[188:191], v[16:19]
	v_mfma_f32_16x16x32_bf16 v[12:15], v[92:95], v[188:191], v[12:15]
	v_mfma_f32_16x16x32_bf16 v[64:67], v[80:83], v[168:171], v[64:67]
	v_mfma_f32_16x16x32_bf16 v[60:63], v[100:103], v[168:171], v[60:63]
	v_mfma_f32_16x16x32_bf16 v[48:51], v[80:83], v[176:179], v[48:51]
	v_mfma_f32_16x16x32_bf16 v[44:47], v[100:103], v[176:179], v[44:47]
	v_mfma_f32_16x16x32_bf16 v[32:35], v[80:83], v[184:187], v[32:35]
	v_mfma_f32_16x16x32_bf16 v[28:31], v[100:103], v[184:187], v[28:31]
	v_mfma_f32_16x16x32_bf16 v[16:19], v[80:83], v[208:211], v[16:19]
	v_mfma_f32_16x16x32_bf16 v[12:15], v[100:103], v[208:211], v[12:15]
	s_setprio 0
	s_setprio 1
	v_mfma_f32_16x16x32_bf16 v[56:59], v[112:115], v[156:159], v[56:59]
	v_mfma_f32_16x16x32_bf16 v[52:55], v[132:135], v[156:159], v[52:55]
	v_mfma_f32_16x16x32_bf16 v[40:43], v[112:115], v[172:175], v[40:43]
	v_mfma_f32_16x16x32_bf16 v[36:39], v[132:135], v[172:175], v[36:39]
	v_mfma_f32_16x16x32_bf16 v[24:27], v[112:115], v[180:183], v[24:27]
	v_mfma_f32_16x16x32_bf16 v[20:23], v[132:135], v[180:183], v[20:23]
	v_mfma_f32_16x16x32_bf16 v[8:11], v[112:115], v[188:191], v[8:11]
	v_mfma_f32_16x16x32_bf16 v[4:7], v[132:135], v[188:191], v[4:7]
	v_mfma_f32_16x16x32_bf16 v[56:59], v[120:123], v[168:171], v[56:59]
	v_mfma_f32_16x16x32_bf16 v[52:55], v[144:147], v[168:171], v[52:55]
	v_mfma_f32_16x16x32_bf16 v[40:43], v[120:123], v[176:179], v[40:43]
	v_mfma_f32_16x16x32_bf16 v[36:39], v[144:147], v[176:179], v[36:39]
	v_mfma_f32_16x16x32_bf16 v[24:27], v[120:123], v[184:187], v[24:27]
	v_mfma_f32_16x16x32_bf16 v[20:23], v[144:147], v[184:187], v[20:23]
	v_mfma_f32_16x16x32_bf16 v[8:11], v[120:123], v[208:211], v[8:11]
	v_mfma_f32_16x16x32_bf16 v[4:7], v[144:147], v[208:211], v[4:7]
	s_setprio 0
	s_barrier
	s_add_i32 s53, s53, 2
	s_add_u32 s44, s44, 0x100
	s_addc_u32 s45, s45, 0
	s_cmp_gt_u32 s53, 41
	s_mov_b64 s[26:27], s[8:9]
	s_cbranch_scc0 .LBB0_480
	s_and_b64 vcc, exec, s[20:21]
	s_cbranch_vccz .LBB0_483
	s_barrier
